# residual epilogue of the N=1024 GEMMs (MIXOUT/FFNOUT/SSMOUT): all gate/x loads of a 16-row block issued before the first wait (was 4 serial round trips per block); on top of v35
# speedup vs baseline: 1.0244x; 1.0115x over previous
; __device__ __forceinline__ f32x4 mfma16(bf16x8 a, bf16x8 b, f32x4 c) { return __builtin_amdgcn_mfma_f32_16x16x32_bf16(a, b, c, 0, 0, 0); }
;     ...
;     for (int kt = 0; kt < nk; ++kt) {
;         lds_sync();
; #pragma unroll
;         for (int i = 0; i < 4; ++i) *(u32x4*)(sW + (srow + i * 32) * GST + skc) = rw[i];
;         lds_sync();
;         const int k0 = (kt + 1 < nk ? kt + 1 : kt) << 6;
;         const int ka = FRAG ? (k0 >> 5) * 512 : k0;
; #pragma unroll
;         for (int i = 0; i < 4; ++i) rw[i] = *(const u32x4*)(wp + (size_t)(i * 32) * ldw + k0);
;         bf16x8 wa[4], wb[4];
; #pragma unroll
;         for (int j = 0; j < 4; ++j) wa[j] = lds16(wr + (j * 16) * GST);
; #pragma unroll
;         for (int j = 0; j < 4; ++j) wb[j] = lds16(wr + ((j + 4) * 16) * GST);
;         __builtin_amdgcn_sched_barrier(0);
;         __builtin_amdgcn_s_setprio(1);
; #pragma unroll
;         for (int j = 0; j < 4; ++j)
; #pragma unroll
;             for (int i = 0; i < MI; ++i) acc[i][j] = mfma16(wa[j], __builtin_bit_cast(bf16x8, ra[i][0]), acc[i][j]);
;         __builtin_amdgcn_sched_barrier(0);
; #pragma unroll
;         for (int j = 0; j < 4; ++j) wa[j] = lds16(wr + (j * 16) * GST + 32);
;         __builtin_amdgcn_sched_barrier(0);
; #pragma unroll
;         for (int j = 0; j < 4; ++j)
; #pragma unroll
;             for (int i = 0; i < MI; ++i) acc[i][j + 4] = mfma16(wb[j], __builtin_bit_cast(bf16x8, ra[i][0]), acc[i][j + 4]);
;         __builtin_amdgcn_sched_barrier(0);
; #pragma unroll
;         for (int i = 0; i < MI; ++i) ra[i][0] = *(const u32x4*)(ap + (size_t)i * ASI + ka);
; #pragma unroll
;         for (int j = 0; j < 4; ++j) wb[j] = lds16(wr + ((j + 4) * 16) * GST + 32);
;         __builtin_amdgcn_sched_barrier(0);
; #pragma unroll
;         for (int j = 0; j < 4; ++j)
; #pragma unroll
;             for (int i = 0; i < MI; ++i) acc[i][j] = mfma16(wa[j], __builtin_bit_cast(bf16x8, ra[i][1]), acc[i][j]);
;         __builtin_amdgcn_sched_barrier(0);
; #pragma unroll
;         for (int j = 0; j < 4; ++j)
; #pragma unroll
;             for (int i = 0; i < MI; ++i) acc[i][j + 4] = mfma16(wb[j], __builtin_bit_cast(bf16x8, ra[i][1]), acc[i][j + 4]);
;         __builtin_amdgcn_s_setprio(0);
;         __builtin_amdgcn_sched_barrier(0);
; #pragma unroll
;         for (int i = 0; i < MI; ++i) ra[i][1] = *(const u32x4*)(ap + (size_t)i * ASI + ka + ASK);
;     }
.LBB0_195:
	v_add_co_u32_e32 v176, vcc, s87, v170
	s_cmpk_lg_i32 s5, 0x400
	s_nop 0
	v_addc_co_u32_e32 v177, vcc, 0, v171, vcc
	v_add_co_u32_e32 v180, vcc, s97, v170
	global_load_dwordx4 v[172:175], v[170:171], off offset:1024
	s_nop 0
	v_addc_co_u32_e32 v181, vcc, 0, v171, vcc
	v_add_co_u32_e32 v170, vcc, s30, v170
	s_cselect_b32 s78, s5, 0x3c0
	s_nop 0
	v_addc_co_u32_e32 v171, vcc, 0, v171, vcc
	global_load_dwordx4 v[176:179], v[176:177], off offset:1024
	s_nop 0
	global_load_dwordx4 v[180:183], v[180:181], off offset:1024
	s_nop 0
	global_load_dwordx4 v[184:187], v[170:171], off offset:1024
	s_waitcnt vmcnt(63) expcnt(7) lgkmcnt(15)
	s_barrier
	s_waitcnt vmcnt(9)
	ds_write_b128 v164, v[136:139]
	ds_write_b128 v164, v[124:127] offset:4608
	ds_write_b128 v164, v[128:131] offset:9216
	s_waitcnt vmcnt(7)
	ds_write_b128 v164, v[144:147] offset:13824
	v_lshl_add_u64 v[124:125], s[78:79], 1, v[160:161]
	v_add_co_u32_e32 v126, vcc, s97, v124
	s_waitcnt lgkmcnt(0)
	s_nop 0
	v_addc_co_u32_e32 v127, vcc, 0, v125, vcc
	v_add_co_u32_e32 v128, vcc, s80, v124
	s_barrier
	s_nop 0
	v_addc_co_u32_e32 v129, vcc, 0, v125, vcc
	v_add_co_u32_e32 v144, vcc, s86, v124
	s_nop 1
	v_addc_co_u32_e32 v145, vcc, 0, v125, vcc
	global_load_dwordx4 v[136:139], v[124:125], off
	s_nop 0
	global_load_dwordx4 v[124:127], v[126:127], off
	s_nop 0
	global_load_dwordx4 v[128:131], v[128:129], off
	s_nop 0
	global_load_dwordx4 v[144:147], v[144:145], off
	ds_read_b128 v[188:191], v169
	ds_read_b128 v[220:223], v169 offset:2304
	ds_read_b128 v[224:227], v169 offset:4608
	ds_read_b128 v[228:231], v169 offset:6912
	ds_read_b128 v[232:235], v169 offset:9216
	ds_read_b128 v[236:239], v169 offset:11520
	ds_read_b128 v[240:243], v169 offset:13824
	ds_read_b128 v[244:247], v169 offset:16128
	s_setprio 1
	s_waitcnt vmcnt(9) lgkmcnt(7)
	v_mfma_f32_16x16x32_bf16 v[156:159], v[188:191], v[112:115], v[156:159]
	s_waitcnt vmcnt(10)
	v_mfma_f32_16x16x32_bf16 v[92:95], v[188:191], v[116:119], v[92:95]
	s_waitcnt vmcnt(9)
	v_mfma_f32_16x16x32_bf16 v[60:63], v[188:191], v[120:123], v[60:63]
	s_waitcnt vmcnt(8)
	v_mfma_f32_16x16x32_bf16 v[28:31], v[188:191], v[132:135], v[28:31]
	s_waitcnt lgkmcnt(6)
	v_mfma_f32_16x16x32_bf16 v[152:155], v[220:223], v[112:115], v[152:155]
	v_mfma_f32_16x16x32_bf16 v[88:91], v[220:223], v[116:119], v[88:91]
	v_mfma_f32_16x16x32_bf16 v[56:59], v[220:223], v[120:123], v[56:59]
	v_mfma_f32_16x16x32_bf16 v[24:27], v[220:223], v[132:135], v[24:27]
	s_waitcnt lgkmcnt(5)
	v_mfma_f32_16x16x32_bf16 v[148:151], v[224:227], v[112:115], v[148:151]
	v_mfma_f32_16x16x32_bf16 v[84:87], v[224:227], v[116:119], v[84:87]
	v_mfma_f32_16x16x32_bf16 v[52:55], v[224:227], v[120:123], v[52:55]
	v_mfma_f32_16x16x32_bf16 v[20:23], v[224:227], v[132:135], v[20:23]
	s_waitcnt lgkmcnt(4)
	v_mfma_f32_16x16x32_bf16 v[140:143], v[228:231], v[112:115], v[140:143]
	v_mfma_f32_16x16x32_bf16 v[80:83], v[228:231], v[116:119], v[80:83]
	v_mfma_f32_16x16x32_bf16 v[48:51], v[228:231], v[120:123], v[48:51]
	v_mfma_f32_16x16x32_bf16 v[16:19], v[228:231], v[132:135], v[16:19]
	ds_read_b128 v[188:191], v169 offset:64
	ds_read_b128 v[220:223], v169 offset:2368
	ds_read_b128 v[224:227], v169 offset:4672
	ds_read_b128 v[228:231], v169 offset:6976
	s_waitcnt lgkmcnt(7)
	v_mfma_f32_16x16x32_bf16 v[108:111], v[232:235], v[112:115], v[108:111]
	v_mfma_f32_16x16x32_bf16 v[76:79], v[232:235], v[116:119], v[76:79]
	v_mfma_f32_16x16x32_bf16 v[44:47], v[232:235], v[120:123], v[44:47]
	v_mfma_f32_16x16x32_bf16 v[12:15], v[232:235], v[132:135], v[12:15]
	s_waitcnt lgkmcnt(6)
	v_mfma_f32_16x16x32_bf16 v[104:107], v[236:239], v[112:115], v[104:107]
	v_mfma_f32_16x16x32_bf16 v[72:75], v[236:239], v[116:119], v[72:75]
	v_mfma_f32_16x16x32_bf16 v[40:43], v[236:239], v[120:123], v[40:43]
	v_mfma_f32_16x16x32_bf16 v[8:11], v[236:239], v[132:135], v[8:11]
	s_waitcnt lgkmcnt(5)
	v_mfma_f32_16x16x32_bf16 v[100:103], v[240:243], v[112:115], v[100:103]
	v_mfma_f32_16x16x32_bf16 v[68:71], v[240:243], v[116:119], v[68:71]
	v_mfma_f32_16x16x32_bf16 v[36:39], v[240:243], v[120:123], v[36:39]
	v_mfma_f32_16x16x32_bf16 v[4:7], v[240:243], v[132:135], v[4:7]
	s_waitcnt lgkmcnt(4)
	v_mfma_f32_16x16x32_bf16 v[96:99], v[244:247], v[112:115], v[96:99]
	v_mfma_f32_16x16x32_bf16 v[64:67], v[244:247], v[116:119], v[64:67]
	v_mfma_f32_16x16x32_bf16 v[32:35], v[244:247], v[120:123], v[32:35]
	v_mfma_f32_16x16x32_bf16 v[0:3], v[244:247], v[132:135], v[0:3]
	s_lshl_b32 s78, s78, 5
	v_lshl_add_u64 v[170:171], v[162:163], 0, s[78:79]
	v_add_co_u32_e32 v112, vcc, s87, v170
	s_nop 1
	v_addc_co_u32_e32 v113, vcc, 0, v171, vcc
	v_add_co_u32_e32 v114, vcc, s97, v170
	s_nop 1
	v_addc_co_u32_e32 v115, vcc, 0, v171, vcc
	v_add_co_u32_e32 v132, vcc, s30, v170
	global_load_dwordx4 v[116:119], v[112:113], off
	global_load_dwordx4 v[120:123], v[114:115], off
	v_addc_co_u32_e32 v133, vcc, 0, v171, vcc
	global_load_dwordx4 v[112:115], v[170:171], off
	s_nop 0
	global_load_dwordx4 v[132:135], v[132:133], off
	ds_read_b128 v[232:235], v169 offset:9280
	ds_read_b128 v[236:239], v169 offset:11584
	ds_read_b128 v[240:243], v169 offset:13888
	ds_read_b128 v[244:247], v169 offset:16192
	s_waitcnt vmcnt(11) lgkmcnt(7)
	v_mfma_f32_16x16x32_bf16 v[156:159], v[188:191], v[172:175], v[156:159]
	s_waitcnt vmcnt(10)
	v_mfma_f32_16x16x32_bf16 v[92:95], v[188:191], v[176:179], v[92:95]
	s_waitcnt vmcnt(9)
	v_mfma_f32_16x16x32_bf16 v[60:63], v[188:191], v[180:183], v[60:63]
	s_waitcnt vmcnt(8)
	v_mfma_f32_16x16x32_bf16 v[28:31], v[188:191], v[184:187], v[28:31]
	s_waitcnt lgkmcnt(6)
; __device__ __forceinline__ int tid_() { int t = threadIdx.x; asm volatile("" : "+v"(t)); return t; }
; __device__ __forceinline__ f32x4 mfma16(bf16x8 a, bf16x8 b, f32x4 c) { return __builtin_amdgcn_mfma_f32_16x16x32_bf16(a, b, c, 0, 0, 0); }
;     ...
;         for (int j = 0; j < 4; ++j)
; #pragma unroll
;             for (int i = 0; i < MI; ++i) acc[i][j] = mfma16(wa[j], __builtin_bit_cast(bf16x8, ra[i][1]), acc[i][j]);
;         __builtin_amdgcn_sched_barrier(0);
; #pragma unroll
;         for (int j = 0; j < 4; ++j)
; #pragma unroll
;             for (int i = 0; i < MI; ++i) acc[i][j + 4] = mfma16(wb[j], __builtin_bit_cast(bf16x8, ra[i][1]), acc[i][j + 4]);
;         __builtin_amdgcn_s_setprio(0);
;         __builtin_amdgcn_sched_barrier(0);
; #pragma unroll
;         for (int i = 0; i < MI; ++i) ra[i][1] = *(const u32x4*)(ap + (size_t)i * ASI + ka + ASK);
;     }
; template <int MI>
; __device__ __forceinline__ void epi_resid(CParams& p, int m0, int n0, const f32x4 (&acc)[MI][8], const float* gate  ) {
;     const int lane = tid_() & 63, wave = tid_() >> 6, l16 = lane & 15, quad = lane >> 4;
; #pragma unroll
;     for (int i = 0; i < MI; ++i) {
;         const int row = m0 + wave * 16 * MI + i * 16 + l16;
;         float* xr = xrow(p, row);
;         const float* g = gate + (size_t)seg_of(row) * 6144;
;         float ss = 0.f;
; #pragma unroll
;         for (int j = 0; j < 8; ++j) {
;             const int col = n0 + j * 16 + quad * 4;
;             const f32x4 gv = *(const f32x4*)(g + col);
;             f32x4 xv = *(f32x4*)(xr + col);
;             xv += gv * acc[i][j];
;             *(f32x4*)(xr + col) = xv;
;             ss += xv[0] * xv[0] + xv[1] * xv[1] + xv[2] * xv[2] + xv[3] * xv[3];
	v_mfma_f32_16x16x32_bf16 v[152:155], v[220:223], v[172:175], v[152:155]
	v_mfma_f32_16x16x32_bf16 v[88:91], v[220:223], v[176:179], v[88:91]
	v_mfma_f32_16x16x32_bf16 v[56:59], v[220:223], v[180:183], v[56:59]
	v_mfma_f32_16x16x32_bf16 v[24:27], v[220:223], v[184:187], v[24:27]
	s_waitcnt lgkmcnt(5)
	v_mfma_f32_16x16x32_bf16 v[148:151], v[224:227], v[172:175], v[148:151]
	v_mfma_f32_16x16x32_bf16 v[84:87], v[224:227], v[176:179], v[84:87]
	v_mfma_f32_16x16x32_bf16 v[52:55], v[224:227], v[180:183], v[52:55]
	v_mfma_f32_16x16x32_bf16 v[20:23], v[224:227], v[184:187], v[20:23]
	s_waitcnt lgkmcnt(4)
	v_mfma_f32_16x16x32_bf16 v[140:143], v[228:231], v[172:175], v[140:143]
	v_mfma_f32_16x16x32_bf16 v[80:83], v[228:231], v[176:179], v[80:83]
	v_mfma_f32_16x16x32_bf16 v[48:51], v[228:231], v[180:183], v[48:51]
	v_mfma_f32_16x16x32_bf16 v[16:19], v[228:231], v[184:187], v[16:19]
	s_waitcnt lgkmcnt(3)
	v_mfma_f32_16x16x32_bf16 v[108:111], v[232:235], v[172:175], v[108:111]
	v_mfma_f32_16x16x32_bf16 v[76:79], v[232:235], v[176:179], v[76:79]
	v_mfma_f32_16x16x32_bf16 v[44:47], v[232:235], v[180:183], v[44:47]
	v_mfma_f32_16x16x32_bf16 v[12:15], v[232:235], v[184:187], v[12:15]
	s_waitcnt lgkmcnt(2)
	v_mfma_f32_16x16x32_bf16 v[104:107], v[236:239], v[172:175], v[104:107]
	v_mfma_f32_16x16x32_bf16 v[72:75], v[236:239], v[176:179], v[72:75]
	v_mfma_f32_16x16x32_bf16 v[40:43], v[236:239], v[180:183], v[40:43]
	v_mfma_f32_16x16x32_bf16 v[8:11], v[236:239], v[184:187], v[8:11]
	s_waitcnt lgkmcnt(1)
	v_mfma_f32_16x16x32_bf16 v[100:103], v[240:243], v[172:175], v[100:103]
	v_mfma_f32_16x16x32_bf16 v[68:71], v[240:243], v[176:179], v[68:71]
	v_mfma_f32_16x16x32_bf16 v[36:39], v[240:243], v[180:183], v[36:39]
	v_mfma_f32_16x16x32_bf16 v[4:7], v[240:243], v[184:187], v[4:7]
	s_waitcnt lgkmcnt(0)
	v_mfma_f32_16x16x32_bf16 v[96:99], v[244:247], v[172:175], v[96:99]
	v_mfma_f32_16x16x32_bf16 v[64:67], v[244:247], v[176:179], v[64:67]
	v_mfma_f32_16x16x32_bf16 v[32:35], v[244:247], v[180:183], v[32:35]
	v_mfma_f32_16x16x32_bf16 v[0:3], v[244:247], v[184:187], v[0:3]
	s_setprio 0
	s_add_i32 s5, s5, 64
	s_cmpk_lg_i32 s5, 0x440
	s_cbranch_scc1 .LBB0_195
	s_waitcnt vmcnt(1)
	v_mov_b32_e32 v112, v167
	v_mov_b32_e32 v113, v167
	s_lshl_b32 s4, s4, 8
	v_mov_b32_e32 v118, s16
	v_bfe_u32 v117, v112, 4, 2
	v_and_b32_e32 v113, 0xffffffc0, v113
	v_and_or_b32 v112, v112, 15, s4
	v_add_u32_e32 v112, v112, v113
	v_ashrrev_i32_e32 v113, 31, v112
	v_cmp_gt_i32_e32 vcc, s34, v112
	v_subrev_co_u32_e64 v114, s[42:43], s34, v112
	v_mov_b32_e32 v119, s45
	v_cndmask_b32_e32 v115, 0, v113, vcc
	v_cndmask_b32_e32 v114, v114, v112, vcc
	v_cndmask_b32_e32 v119, v118, v119, vcc
	v_mov_b32_e32 v118, s15
	v_mov_b32_e32 v121, s44
	s_movk_i32 s2, 0x1fff
	v_cndmask_b32_e64 v116, v213, v214, s[42:43]
	v_cndmask_b32_e32 v118, v118, v121, vcc
	v_lshlrev_b64 v[114:115], 12, v[114:115]
	v_cmp_lt_i32_e32 vcc, s2, v112
	s_lshl_b32 s5, s6, 7
	v_lshl_add_u64 v[114:115], v[118:119], 0, v[114:115]
	v_cndmask_b32_e32 v118, 0, v116, vcc
	v_lshl_or_b32 v120, v117, 2, s5
	v_lshlrev_b32_e32 v164, 2, v118
	v_lshl_add_u64 v[118:119], s[48:49], 0, v[164:165]
	v_lshlrev_b32_e32 v164, 2, v120
	v_lshl_add_u64 v[146:147], v[118:119], 0, v[164:165]
	v_lshl_add_u64 v[114:115], v[114:115], 0, v[164:165]
	global_load_dwordx4 v[160:163], v[146:147], off
	global_load_dwordx4 v[172:175], v[114:115], off
	global_load_dwordx4 v[176:179], v[114:115], off offset:64
	global_load_dwordx4 v[180:183], v[146:147], off offset:64
	global_load_dwordx4 v[184:187], v[146:147], off offset:128
	global_load_dwordx4 v[188:191], v[114:115], off offset:128
	global_load_dwordx4 v[220:223], v[114:115], off offset:192
	global_load_dwordx4 v[224:227], v[146:147], off offset:192
	global_load_dwordx4 v[228:231], v[146:147], off offset:256
	global_load_dwordx4 v[232:235], v[114:115], off offset:256
	global_load_dwordx4 v[236:239], v[114:115], off offset:320
	global_load_dwordx4 v[240:243], v[146:147], off offset:320
	v_cmp_lt_i32_e32 vcc, v204, v199
	s_lshl_b32 s4, s6, 2
	s_add_u32 s4, s46, s4
	s_addc_u32 s5, s47, 0
	s_waitcnt vmcnt(10)
	v_pk_fma_f32 v[120:121], v[158:159], v[162:163], v[174:175]
	v_pk_fma_f32 v[118:119], v[156:157], v[160:161], v[172:173]
	global_store_dwordx4 v[114:115], v[118:121], off
	s_waitcnt vmcnt(8)
	v_pk_fma_f32 v[124:125], v[154:155], v[182:183], v[178:179]
	v_pk_fma_f32 v[122:123], v[152:153], v[180:181], v[176:177]
	global_store_dwordx4 v[114:115], v[122:125], off offset:64
	s_waitcnt vmcnt(6)
	v_pk_fma_f32 v[128:129], v[150:151], v[186:187], v[190:191]
	v_pk_fma_f32 v[126:127], v[148:149], v[184:185], v[188:189]
	global_store_dwordx4 v[114:115], v[126:129], off offset:128
	s_waitcnt vmcnt(4)
	v_pk_fma_f32 v[132:133], v[142:143], v[226:227], v[222:223]
	v_pk_fma_f32 v[130:131], v[140:141], v[224:225], v[220:221]
	global_store_dwordx4 v[114:115], v[130:133], off offset:192
	s_waitcnt vmcnt(2)
	v_pk_fma_f32 v[110:111], v[110:111], v[230:231], v[234:235]
	v_pk_fma_f32 v[108:109], v[108:109], v[228:229], v[232:233]
	global_store_dwordx4 v[114:115], v[108:111], off offset:256
	s_waitcnt vmcnt(0)
	v_pk_fma_f32 v[106:107], v[106:107], v[242:243], v[238:239]
	v_pk_fma_f32 v[104:105], v[104:105], v[240:241], v[236:237]
	global_store_dwordx4 v[114:115], v[104:107], off offset:320
	global_load_dwordx4 v[134:137], v[146:147], off offset:384
	global_load_dwordx4 v[138:141], v[114:115], off offset:384
	global_load_dwordx4 v[142:145], v[114:115], off offset:448
	s_waitcnt vmcnt(1)
; __device__ __forceinline__ int tid_() { int t = threadIdx.x; asm volatile("" : "+v"(t)); return t; }
; template <int MI>
; __device__ __forceinline__ void epi_resid(CParams& p, int m0, int n0, const f32x4 (&acc)[MI][8], const float* gate  ) {
;     const int lane = tid_() & 63, wave = tid_() >> 6, l16 = lane & 15, quad = lane >> 4;
; #pragma unroll
;     for (int i = 0; i < MI; ++i) {
;         const int row = m0 + wave * 16 * MI + i * 16 + l16;
;         float* xr = xrow(p, row);
;         const float* g = gate + (size_t)seg_of(row) * 6144;
;         float ss = 0.f;
; #pragma unroll
;         for (int j = 0; j < 8; ++j) {
;             const int col = n0 + j * 16 + quad * 4;
;             const f32x4 gv = *(const f32x4*)(g + col);
;             f32x4 xv = *(f32x4*)(xr + col);
;             xv += gv * acc[i][j];
;             *(f32x4*)(xr + col) = xv;
;             ss += xv[0] * xv[0] + xv[1] * xv[1] + xv[2] * xv[2] + xv[3] * xv[3];
;         }
;         ss += __shfl_xor(ss, 16); ss += __shfl_xor(ss, 32);
;         if (quad == 0) ((float*)(p.ws + WS_PART))[(size_t)row * 8 + (n0 >> 7)] = ss;
;         __builtin_amdgcn_sched_barrier(0);
;     }
	v_pk_fma_f32 v[136:137], v[102:103], v[136:137], v[140:141]
	v_pk_fma_f32 v[134:135], v[100:101], v[134:135], v[138:139]
	global_store_dwordx4 v[114:115], v[134:137], off offset:384
	global_load_dwordx4 v[138:141], v[146:147], off offset:448
	v_cndmask_b32_e32 v100, v197, v204, vcc
	v_lshlrev_b32_e32 v102, 2, v100
	v_mul_f32_e32 v100, v119, v119
	v_mul_f32_e32 v101, v123, v123
	v_fmac_f32_e32 v100, v118, v118
	v_fmac_f32_e32 v101, v122, v122
	v_fmac_f32_e32 v100, v120, v120
	v_fmac_f32_e32 v101, v124, v124
	v_fmac_f32_e32 v100, v121, v121
	v_fmac_f32_e32 v101, v125, v125
	v_add_f32_e32 v100, v100, v101
	v_mul_f32_e32 v101, v127, v127
	v_fmac_f32_e32 v101, v126, v126
	v_fmac_f32_e32 v101, v128, v128
	v_fmac_f32_e32 v101, v129, v129
	v_add_f32_e32 v100, v100, v101
	v_mul_f32_e32 v101, v131, v131
	v_fmac_f32_e32 v101, v130, v130
	v_fmac_f32_e32 v101, v132, v132
	v_fmac_f32_e32 v101, v133, v133
	v_add_f32_e32 v100, v100, v101
	v_mul_f32_e32 v101, v109, v109
	v_fmac_f32_e32 v101, v108, v108
	v_fmac_f32_e32 v101, v110, v110
	v_fmac_f32_e32 v101, v111, v111
	v_add_f32_e32 v100, v100, v101
	v_mul_f32_e32 v101, v105, v105
	v_fmac_f32_e32 v101, v104, v104
	v_fmac_f32_e32 v101, v106, v106
	v_fmac_f32_e32 v101, v107, v107
	v_add_f32_e32 v100, v100, v101
	v_mul_f32_e32 v101, v135, v135
	v_fmac_f32_e32 v101, v134, v134
	v_fmac_f32_e32 v101, v136, v136
	v_fmac_f32_e32 v101, v137, v137
	v_add_f32_e32 v103, v100, v101
	v_cmp_lt_i32_e32 vcc, v205, v199
	s_waitcnt vmcnt(0)
	v_pk_fma_f32 v[100:101], v[98:99], v[140:141], v[144:145]
	v_pk_fma_f32 v[98:99], v[96:97], v[138:139], v[142:143]
	global_store_dwordx4 v[114:115], v[98:101], off offset:448
	v_mul_f32_e32 v96, v99, v99
	v_fmac_f32_e32 v96, v98, v98
	v_fmac_f32_e32 v96, v100, v100
	v_fmac_f32_e32 v96, v101, v101
	v_add_f32_e32 v96, v103, v96
	ds_bpermute_b32 v97, v102, v96
	v_cndmask_b32_e32 v103, v197, v205, vcc
	v_lshlrev_b32_e32 v103, 2, v103
	v_cmp_eq_u32_e32 vcc, 0, v117
	s_waitcnt lgkmcnt(0)
	v_add_f32_e32 v96, v96, v97
	ds_bpermute_b32 v97, v103, v96
	s_and_saveexec_b64 s[6:7], vcc
	s_cbranch_execz .LBB0_198
	v_lshlrev_b64 v[98:99], 5, v[112:113]
	v_lshl_add_u64 v[98:99], s[4:5], 0, v[98:99]
	s_waitcnt lgkmcnt(0)
	v_add_f32_e32 v96, v96, v97
	global_store_dword v[98:99], v96, off
.LBB0_198:
	s_or_b64 exec, exec, s[6:7]
	v_or_b32_e32 v96, 16, v112
	v_cmp_gt_i32_e64 s[42:43], s34, v96
	v_add_u32_e32 v98, 0xffffc010, v112
	s_waitcnt lgkmcnt(0)
	v_ashrrev_i32_e32 v97, 31, v96
	v_mov_b32_e32 v100, s16
	v_mov_b32_e32 v101, s45
	v_cndmask_b32_e64 v99, 0, v97, s[42:43]
	v_cndmask_b32_e64 v98, v98, v96, s[42:43]
	v_cndmask_b32_e64 v101, v100, v101, s[42:43]
	v_mov_b32_e32 v100, s15
	v_mov_b32_e32 v104, s44
	v_cndmask_b32_e64 v100, v100, v104, s[42:43]
	v_lshlrev_b64 v[98:99], 12, v[98:99]
	v_cmp_lt_i32_e64 s[42:43], s2, v96
	v_lshl_add_u64 v[98:99], v[100:101], 0, v[98:99]
	v_mov_b32_e32 v101, v165
	v_cndmask_b32_e64 v100, 0, v116, s[42:43]
	v_lshlrev_b32_e32 v100, 2, v100
	v_lshl_add_u64 v[100:101], s[48:49], 0, v[100:101]
	v_lshl_add_u64 v[100:101], v[100:101], 0, v[164:165]
	v_lshl_add_u64 v[98:99], v[98:99], 0, v[164:165]
	global_load_dwordx4 v[120:123], v[100:101], off
	global_load_dwordx4 v[124:127], v[98:99], off
	global_load_dwordx4 v[128:131], v[100:101], off offset:64
	global_load_dwordx4 v[132:135], v[98:99], off offset:64
	global_load_dwordx4 v[136:139], v[100:101], off offset:128
	global_load_dwordx4 v[140:143], v[98:99], off offset:128
	global_load_dwordx4 v[144:147], v[100:101], off offset:192
	global_load_dwordx4 v[148:151], v[98:99], off offset:192
	global_load_dwordx4 v[152:155], v[100:101], off offset:256
	global_load_dwordx4 v[156:159], v[98:99], off offset:256
	global_load_dwordx4 v[160:163], v[100:101], off offset:320
	global_load_dwordx4 v[172:175], v[98:99], off offset:320
	global_load_dwordx4 v[176:179], v[100:101], off offset:384
	global_load_dwordx4 v[180:183], v[98:99], off offset:384
	global_load_dwordx4 v[184:187], v[100:101], off offset:448
	global_load_dwordx4 v[188:191], v[98:99], off offset:448
	s_waitcnt vmcnt(14)
	v_pk_fma_f32 v[92:93], v[92:93], v[120:121], v[124:125]
	s_nop 0
	v_mul_f32_e32 v108, v93, v93
	v_pk_fma_f32 v[94:95], v[94:95], v[122:123], v[126:127]
	v_fmac_f32_e32 v108, v92, v92
	global_store_dwordx4 v[98:99], v[92:95], off
	v_fmac_f32_e32 v108, v94, v94
	v_fmac_f32_e32 v108, v95, v95
	s_waitcnt vmcnt(12)
	v_pk_fma_f32 v[90:91], v[90:91], v[130:131], v[134:135]
	v_pk_fma_f32 v[88:89], v[88:89], v[128:129], v[132:133]
	global_store_dwordx4 v[98:99], v[88:91], off offset:64
	s_nop 1
	v_mul_f32_e32 v89, v89, v89
	v_fmac_f32_e32 v89, v88, v88
	v_fmac_f32_e32 v89, v90, v90
	v_fmac_f32_e32 v89, v91, v91
	v_add_f32_e32 v104, v108, v89
	s_waitcnt vmcnt(10)
	v_pk_fma_f32 v[86:87], v[86:87], v[138:139], v[142:143]
	v_pk_fma_f32 v[84:85], v[84:85], v[136:137], v[140:141]
	global_store_dwordx4 v[98:99], v[84:87], off offset:128
	s_nop 1
	v_mul_f32_e32 v85, v85, v85
	v_fmac_f32_e32 v85, v84, v84
	v_fmac_f32_e32 v85, v86, v86
	v_fmac_f32_e32 v85, v87, v87
	v_add_f32_e32 v92, v104, v85
	s_waitcnt vmcnt(8)
	v_pk_fma_f32 v[82:83], v[82:83], v[146:147], v[150:151]
	v_pk_fma_f32 v[80:81], v[80:81], v[144:145], v[148:149]
	global_store_dwordx4 v[98:99], v[80:83], off offset:192
	s_nop 1
	v_mul_f32_e32 v81, v81, v81
	v_fmac_f32_e32 v81, v80, v80
	v_fmac_f32_e32 v81, v82, v82
	v_fmac_f32_e32 v81, v83, v83
	v_add_f32_e32 v88, v92, v81
	s_waitcnt vmcnt(6)
	v_pk_fma_f32 v[78:79], v[78:79], v[154:155], v[158:159]
	v_pk_fma_f32 v[76:77], v[76:77], v[152:153], v[156:157]
	global_store_dwordx4 v[98:99], v[76:79], off offset:256
	s_nop 1
	v_mul_f32_e32 v77, v77, v77
	v_fmac_f32_e32 v77, v76, v76
	v_fmac_f32_e32 v77, v78, v78
	v_fmac_f32_e32 v77, v79, v79
	v_add_f32_e32 v84, v88, v77
	s_waitcnt vmcnt(4)
	v_pk_fma_f32 v[74:75], v[74:75], v[162:163], v[174:175]
	v_pk_fma_f32 v[72:73], v[72:73], v[160:161], v[172:173]
	global_store_dwordx4 v[98:99], v[72:75], off offset:320
	s_nop 1
	v_mul_f32_e32 v73, v73, v73
	v_fmac_f32_e32 v73, v72, v72
	v_fmac_f32_e32 v73, v74, v74
	v_fmac_f32_e32 v73, v75, v75
	v_add_f32_e32 v80, v84, v73
	s_waitcnt vmcnt(2)
	v_pk_fma_f32 v[70:71], v[70:71], v[178:179], v[182:183]
	v_pk_fma_f32 v[68:69], v[68:69], v[176:177], v[180:181]
	global_store_dwordx4 v[98:99], v[68:71], off offset:384
	s_nop 1
	v_mul_f32_e32 v69, v69, v69
	v_fmac_f32_e32 v69, v68, v68
	v_fmac_f32_e32 v69, v70, v70
	v_fmac_f32_e32 v69, v71, v71
	v_add_f32_e32 v76, v80, v69
	s_waitcnt vmcnt(0)
	v_pk_fma_f32 v[66:67], v[66:67], v[186:187], v[190:191]
	v_pk_fma_f32 v[64:65], v[64:65], v[184:185], v[188:189]
	global_store_dwordx4 v[98:99], v[64:67], off offset:448
	s_nop 1
	v_mul_f32_e32 v65, v65, v65
	v_fmac_f32_e32 v65, v64, v64
	v_fmac_f32_e32 v65, v66, v66
	v_fmac_f32_e32 v65, v67, v67
	v_add_f32_e32 v64, v76, v65
	ds_bpermute_b32 v65, v102, v64
	s_waitcnt lgkmcnt(0)
	v_add_f32_e32 v64, v64, v65
	ds_bpermute_b32 v65, v103, v64
	s_and_saveexec_b64 s[6:7], vcc
	s_cbranch_execz .LBB0_200
; template <int MI>
; __device__ __forceinline__ void epi_resid(CParams& p, int m0, int n0, const f32x4 (&acc)[MI][8], const float* gate  ) {
;     ...
;     for (int i = 0; i < MI; ++i) {
;         const int row = m0 + wave * 16 * MI + i * 16 + l16;
;         float* xr = xrow(p, row);
;         const float* g = gate + (size_t)seg_of(row) * 6144;
;         float ss = 0.f;
; #pragma unroll
;         for (int j = 0; j < 8; ++j) {
;             const int col = n0 + j * 16 + quad * 4;
;             const f32x4 gv = *(const f32x4*)(g + col);
;             f32x4 xv = *(f32x4*)(xr + col);
;             xv += gv * acc[i][j];
;             *(f32x4*)(xr + col) = xv;
;             ss += xv[0] * xv[0] + xv[1] * xv[1] + xv[2] * xv[2] + xv[3] * xv[3];
;         }
;         ss += __shfl_xor(ss, 16); ss += __shfl_xor(ss, 32);
;         if (quad == 0) ((float*)(p.ws + WS_PART))[(size_t)row * 8 + (n0 >> 7)] = ss;
;         __builtin_amdgcn_sched_barrier(0);
;     }
	v_lshlrev_b64 v[66:67], 5, v[96:97]
	v_lshl_add_u64 v[66:67], s[4:5], 0, v[66:67]
	s_waitcnt lgkmcnt(0)
	v_add_f32_e32 v64, v64, v65
	global_store_dword v[66:67], v64, off
.LBB0_200:
	s_or_b64 exec, exec, s[6:7]
	v_or_b32_e32 v64, 32, v112
	v_cmp_gt_i32_e64 s[42:43], s34, v64
	v_add_u32_e32 v66, 0xffffc020, v112
	s_waitcnt lgkmcnt(0)
	v_ashrrev_i32_e32 v65, 31, v64
	v_mov_b32_e32 v68, s16
	v_mov_b32_e32 v69, s45
	v_cndmask_b32_e64 v67, 0, v65, s[42:43]
	v_cndmask_b32_e64 v66, v66, v64, s[42:43]
	v_cndmask_b32_e64 v69, v68, v69, s[42:43]
	v_mov_b32_e32 v68, s15
	v_mov_b32_e32 v70, s44
	v_cndmask_b32_e64 v68, v68, v70, s[42:43]
	v_lshlrev_b64 v[66:67], 12, v[66:67]
	v_cmp_lt_i32_e64 s[42:43], s2, v64
	v_lshl_add_u64 v[66:67], v[68:69], 0, v[66:67]
	v_mov_b32_e32 v69, v165
	v_cndmask_b32_e64 v68, 0, v116, s[42:43]
	v_lshlrev_b32_e32 v68, 2, v68
	v_lshl_add_u64 v[68:69], s[48:49], 0, v[68:69]
	v_lshl_add_u64 v[68:69], v[68:69], 0, v[164:165]
	v_lshl_add_u64 v[66:67], v[66:67], 0, v[164:165]
	global_load_dwordx4 v[80:83], v[68:69], off
	global_load_dwordx4 v[84:87], v[66:67], off
	global_load_dwordx4 v[88:91], v[68:69], off offset:64
	global_load_dwordx4 v[92:95], v[66:67], off offset:64
	global_load_dwordx4 v[96:99], v[68:69], off offset:128
	global_load_dwordx4 v[104:107], v[66:67], off offset:128
	global_load_dwordx4 v[108:111], v[68:69], off offset:192
	global_load_dwordx4 v[120:123], v[66:67], off offset:192
	global_load_dwordx4 v[124:127], v[68:69], off offset:256
	global_load_dwordx4 v[128:131], v[66:67], off offset:256
	global_load_dwordx4 v[132:135], v[68:69], off offset:320
	global_load_dwordx4 v[136:139], v[66:67], off offset:320
	global_load_dwordx4 v[140:143], v[68:69], off offset:384
	global_load_dwordx4 v[144:147], v[66:67], off offset:384
	global_load_dwordx4 v[148:151], v[68:69], off offset:448
	global_load_dwordx4 v[152:155], v[66:67], off offset:448
	s_waitcnt vmcnt(14)
	v_pk_fma_f32 v[60:61], v[60:61], v[80:81], v[84:85]
	s_nop 0
	v_mul_f32_e32 v74, v61, v61
	v_pk_fma_f32 v[62:63], v[62:63], v[82:83], v[86:87]
	v_fmac_f32_e32 v74, v60, v60
	global_store_dwordx4 v[66:67], v[60:63], off
	v_fmac_f32_e32 v74, v62, v62
	v_fmac_f32_e32 v74, v63, v63
	s_waitcnt vmcnt(12)
	v_pk_fma_f32 v[58:59], v[58:59], v[90:91], v[94:95]
	v_pk_fma_f32 v[56:57], v[56:57], v[88:89], v[92:93]
	global_store_dwordx4 v[66:67], v[56:59], off offset:64
	s_nop 1
	v_mul_f32_e32 v57, v57, v57
	v_fmac_f32_e32 v57, v56, v56
	v_fmac_f32_e32 v57, v58, v58
	v_fmac_f32_e32 v57, v59, v59
	v_add_f32_e32 v70, v74, v57
	s_waitcnt vmcnt(10)
	v_pk_fma_f32 v[54:55], v[54:55], v[98:99], v[106:107]
	v_pk_fma_f32 v[52:53], v[52:53], v[96:97], v[104:105]
	global_store_dwordx4 v[66:67], v[52:55], off offset:128
	s_nop 1
	v_mul_f32_e32 v53, v53, v53
	v_fmac_f32_e32 v53, v52, v52
	v_fmac_f32_e32 v53, v54, v54
	v_fmac_f32_e32 v53, v55, v55
	v_add_f32_e32 v60, v70, v53
	s_waitcnt vmcnt(8)
	v_pk_fma_f32 v[50:51], v[50:51], v[110:111], v[122:123]
	v_pk_fma_f32 v[48:49], v[48:49], v[108:109], v[120:121]
	global_store_dwordx4 v[66:67], v[48:51], off offset:192
	s_nop 1
	v_mul_f32_e32 v49, v49, v49
	v_fmac_f32_e32 v49, v48, v48
	v_fmac_f32_e32 v49, v50, v50
	v_fmac_f32_e32 v49, v51, v51
	v_add_f32_e32 v56, v60, v49
	s_waitcnt vmcnt(6)
	v_pk_fma_f32 v[46:47], v[46:47], v[126:127], v[130:131]
	v_pk_fma_f32 v[44:45], v[44:45], v[124:125], v[128:129]
	global_store_dwordx4 v[66:67], v[44:47], off offset:256
	s_nop 1
	v_mul_f32_e32 v45, v45, v45
	v_fmac_f32_e32 v45, v44, v44
	v_fmac_f32_e32 v45, v46, v46
	v_fmac_f32_e32 v45, v47, v47
	v_add_f32_e32 v52, v56, v45
	s_waitcnt vmcnt(4)
	v_pk_fma_f32 v[42:43], v[42:43], v[134:135], v[138:139]
	v_pk_fma_f32 v[40:41], v[40:41], v[132:133], v[136:137]
	global_store_dwordx4 v[66:67], v[40:43], off offset:320
	s_nop 1
	v_mul_f32_e32 v41, v41, v41
	v_fmac_f32_e32 v41, v40, v40
	v_fmac_f32_e32 v41, v42, v42
	v_fmac_f32_e32 v41, v43, v43
	v_add_f32_e32 v48, v52, v41
	s_waitcnt vmcnt(2)
	v_pk_fma_f32 v[38:39], v[38:39], v[142:143], v[146:147]
	v_pk_fma_f32 v[36:37], v[36:37], v[140:141], v[144:145]
	global_store_dwordx4 v[66:67], v[36:39], off offset:384
	s_nop 1
	v_mul_f32_e32 v37, v37, v37
	v_fmac_f32_e32 v37, v36, v36
	v_fmac_f32_e32 v37, v38, v38
	v_fmac_f32_e32 v37, v39, v39
	v_add_f32_e32 v44, v48, v37
	s_waitcnt vmcnt(0)
	v_pk_fma_f32 v[34:35], v[34:35], v[150:151], v[154:155]
	v_pk_fma_f32 v[32:33], v[32:33], v[148:149], v[152:153]
	global_store_dwordx4 v[66:67], v[32:35], off offset:448
	s_nop 1
	v_mul_f32_e32 v33, v33, v33
	v_fmac_f32_e32 v33, v32, v32
	v_fmac_f32_e32 v33, v34, v34
	v_fmac_f32_e32 v33, v35, v35
	v_add_f32_e32 v32, v44, v33
	ds_bpermute_b32 v33, v102, v32
	s_waitcnt lgkmcnt(0)
	v_add_f32_e32 v32, v32, v33
	ds_bpermute_b32 v33, v103, v32
	s_and_saveexec_b64 s[6:7], vcc
	s_mov_b32 s39, s0
	s_cbranch_execz .LBB0_202
	v_lshlrev_b64 v[34:35], 5, v[64:65]
	v_lshl_add_u64 v[34:35], s[4:5], 0, v[34:35]
	s_waitcnt lgkmcnt(0)
	v_add_f32_e32 v32, v32, v33
	global_store_dword v[34:35], v32, off
; template <int MI>
; __device__ __forceinline__ void epi_resid(CParams& p, int m0, int n0, const f32x4 (&acc)[MI][8], const float* gate  ) {
;     ...
;     for (int i = 0; i < MI; ++i) {
;         const int row = m0 + wave * 16 * MI + i * 16 + l16;
;         float* xr = xrow(p, row);
;         const float* g = gate + (size_t)seg_of(row) * 6144;
;         float ss = 0.f;
; #pragma unroll
;         for (int j = 0; j < 8; ++j) {
;             const int col = n0 + j * 16 + quad * 4;
;             const f32x4 gv = *(const f32x4*)(g + col);
;             f32x4 xv = *(f32x4*)(xr + col);
;             xv += gv * acc[i][j];
;             *(f32x4*)(xr + col) = xv;
;             ss += xv[0] * xv[0] + xv[1] * xv[1] + xv[2] * xv[2] + xv[3] * xv[3];
;         }
;         ss += __shfl_xor(ss, 16); ss += __shfl_xor(ss, 32);
;         if (quad == 0) ((float*)(p.ws + WS_PART))[(size_t)row * 8 + (n0 >> 7)] = ss;
;         __builtin_amdgcn_sched_barrier(0);
;     }
.LBB0_202:
	s_or_b64 exec, exec, s[6:7]
	v_or_b32_e32 v32, 48, v112
	v_cmp_gt_i32_e64 s[42:43], s34, v32
	v_add_u32_e32 v34, 0xffffc030, v112
	s_waitcnt lgkmcnt(0)
	v_ashrrev_i32_e32 v33, 31, v32
	v_mov_b32_e32 v36, s16
	v_mov_b32_e32 v37, s45
	v_cndmask_b32_e64 v35, 0, v33, s[42:43]
	v_cndmask_b32_e64 v34, v34, v32, s[42:43]
	v_cndmask_b32_e64 v37, v36, v37, s[42:43]
	v_mov_b32_e32 v36, s15
	v_mov_b32_e32 v38, s44
	v_cndmask_b32_e64 v36, v36, v38, s[42:43]
	v_lshlrev_b64 v[34:35], 12, v[34:35]
	v_cmp_lt_i32_e64 s[42:43], s2, v32
	v_lshl_add_u64 v[34:35], v[36:37], 0, v[34:35]
	v_mov_b32_e32 v37, v165
	v_cndmask_b32_e64 v36, 0, v116, s[42:43]
	v_lshlrev_b32_e32 v36, 2, v36
	v_lshl_add_u64 v[36:37], s[48:49], 0, v[36:37]
	v_lshl_add_u64 v[36:37], v[36:37], 0, v[164:165]
	v_lshl_add_u64 v[34:35], v[34:35], 0, v[164:165]
	global_load_dwordx4 v[48:51], v[36:37], off
	global_load_dwordx4 v[52:55], v[34:35], off
	global_load_dwordx4 v[56:59], v[36:37], off offset:64
	global_load_dwordx4 v[60:63], v[34:35], off offset:64
	global_load_dwordx4 v[64:67], v[36:37], off offset:128
	global_load_dwordx4 v[68:71], v[34:35], off offset:128
	global_load_dwordx4 v[72:75], v[36:37], off offset:192
	global_load_dwordx4 v[76:79], v[34:35], off offset:192
	global_load_dwordx4 v[80:83], v[36:37], off offset:256
	global_load_dwordx4 v[84:87], v[34:35], off offset:256
	global_load_dwordx4 v[88:91], v[36:37], off offset:320
	global_load_dwordx4 v[92:95], v[34:35], off offset:320
	global_load_dwordx4 v[96:99], v[36:37], off offset:384
	global_load_dwordx4 v[104:107], v[34:35], off offset:384
	global_load_dwordx4 v[108:111], v[36:37], off offset:448
	global_load_dwordx4 v[120:123], v[34:35], off offset:448
	s_waitcnt vmcnt(14)
	v_pk_fma_f32 v[28:29], v[28:29], v[48:49], v[52:53]
	s_nop 0
	v_mul_f32_e32 v42, v29, v29
	v_pk_fma_f32 v[30:31], v[30:31], v[50:51], v[54:55]
	v_fmac_f32_e32 v42, v28, v28
	global_store_dwordx4 v[34:35], v[28:31], off
	v_fmac_f32_e32 v42, v30, v30
	v_fmac_f32_e32 v42, v31, v31
	s_waitcnt vmcnt(12)
	v_pk_fma_f32 v[26:27], v[26:27], v[58:59], v[62:63]
	v_pk_fma_f32 v[24:25], v[24:25], v[56:57], v[60:61]
	global_store_dwordx4 v[34:35], v[24:27], off offset:64
	s_nop 1
	v_mul_f32_e32 v25, v25, v25
	v_fmac_f32_e32 v25, v24, v24
	v_fmac_f32_e32 v25, v26, v26
	v_fmac_f32_e32 v25, v27, v27
	v_add_f32_e32 v38, v42, v25
	s_waitcnt vmcnt(10)
	v_pk_fma_f32 v[22:23], v[22:23], v[66:67], v[70:71]
	v_pk_fma_f32 v[20:21], v[20:21], v[64:65], v[68:69]
	global_store_dwordx4 v[34:35], v[20:23], off offset:128
	s_nop 1
	v_mul_f32_e32 v21, v21, v21
	v_fmac_f32_e32 v21, v20, v20
	v_fmac_f32_e32 v21, v22, v22
	v_fmac_f32_e32 v21, v23, v23
	v_add_f32_e32 v28, v38, v21
	s_waitcnt vmcnt(8)
	v_pk_fma_f32 v[18:19], v[18:19], v[74:75], v[78:79]
	v_pk_fma_f32 v[16:17], v[16:17], v[72:73], v[76:77]
	global_store_dwordx4 v[34:35], v[16:19], off offset:192
	s_nop 1
	v_mul_f32_e32 v17, v17, v17
	v_fmac_f32_e32 v17, v16, v16
	v_fmac_f32_e32 v17, v18, v18
	v_fmac_f32_e32 v17, v19, v19
	v_add_f32_e32 v24, v28, v17
	s_waitcnt vmcnt(6)
	v_pk_fma_f32 v[14:15], v[14:15], v[82:83], v[86:87]
	v_pk_fma_f32 v[12:13], v[12:13], v[80:81], v[84:85]
	global_store_dwordx4 v[34:35], v[12:15], off offset:256
	s_nop 1
	v_mul_f32_e32 v13, v13, v13
	v_fmac_f32_e32 v13, v12, v12
	v_fmac_f32_e32 v13, v14, v14
	v_fmac_f32_e32 v13, v15, v15
	v_add_f32_e32 v20, v24, v13
	s_waitcnt vmcnt(4)
	v_pk_fma_f32 v[10:11], v[10:11], v[90:91], v[94:95]
	v_pk_fma_f32 v[8:9], v[8:9], v[88:89], v[92:93]
	global_store_dwordx4 v[34:35], v[8:11], off offset:320
	s_nop 1
	v_mul_f32_e32 v9, v9, v9
	v_fmac_f32_e32 v9, v8, v8
	v_fmac_f32_e32 v9, v10, v10
	v_fmac_f32_e32 v9, v11, v11
	v_add_f32_e32 v16, v20, v9
	s_waitcnt vmcnt(2)
	v_pk_fma_f32 v[6:7], v[6:7], v[98:99], v[106:107]
	v_pk_fma_f32 v[4:5], v[4:5], v[96:97], v[104:105]
	global_store_dwordx4 v[34:35], v[4:7], off offset:384
	s_nop 1
	v_mul_f32_e32 v5, v5, v5
	v_fmac_f32_e32 v5, v4, v4
	v_fmac_f32_e32 v5, v6, v6
	v_fmac_f32_e32 v5, v7, v7
	v_add_f32_e32 v12, v16, v5
	s_waitcnt vmcnt(0)
	v_pk_fma_f32 v[2:3], v[2:3], v[110:111], v[122:123]
	v_pk_fma_f32 v[0:1], v[0:1], v[108:109], v[120:121]
	global_store_dwordx4 v[34:35], v[0:3], off offset:448
	s_nop 1
	v_mul_f32_e32 v1, v1, v1
	v_fmac_f32_e32 v1, v0, v0
	v_fmac_f32_e32 v1, v2, v2
	v_fmac_f32_e32 v1, v3, v3
	v_add_f32_e32 v0, v12, v1
	ds_bpermute_b32 v1, v102, v0
	s_waitcnt lgkmcnt(0)
	v_add_f32_e32 v0, v0, v1
	ds_bpermute_b32 v1, v103, v0
	s_and_saveexec_b64 s[6:7], vcc
	s_cbranch_execz .LBB0_185
	v_lshlrev_b64 v[2:3], 5, v[32:33]
	v_lshl_add_u64 v[2:3], s[4:5], 0, v[2:3]
	s_waitcnt lgkmcnt(0)
	v_add_f32_e32 v0, v0, v1
	global_store_dword v[2:3], v0, off
	s_branch .LBB0_185

; __device__ __forceinline__ f32x4 mfma16(bf16x8 a, bf16x8 b, f32x4 c) { return __builtin_amdgcn_mfma_f32_16x16x32_bf16(a, b, c, 0, 0, 0); }
;     ...
;     for (int kt = 0; kt < nk; ++kt) {
;         lds_sync();
; #pragma unroll
;         for (int i = 0; i < 4; ++i) *(u32x4*)(sW + (srow + i * 32) * GST + skc) = rw[i];
;         lds_sync();
;         const int k0 = (kt + 1 < nk ? kt + 1 : kt) << 6;
;         const int ka = FRAG ? (k0 >> 5) * 512 : k0;
; #pragma unroll
;         for (int i = 0; i < 4; ++i) rw[i] = *(const u32x4*)(wp + (size_t)(i * 32) * ldw + k0);
;         bf16x8 wa[4], wb[4];
; #pragma unroll
;         for (int j = 0; j < 4; ++j) wa[j] = lds16(wr + (j * 16) * GST);
; #pragma unroll
;         for (int j = 0; j < 4; ++j) wb[j] = lds16(wr + ((j + 4) * 16) * GST);
;         __builtin_amdgcn_sched_barrier(0);
;         __builtin_amdgcn_s_setprio(1);
; #pragma unroll
;         for (int j = 0; j < 4; ++j)
; #pragma unroll
;             for (int i = 0; i < MI; ++i) acc[i][j] = mfma16(wa[j], __builtin_bit_cast(bf16x8, ra[i][0]), acc[i][j]);
;         __builtin_amdgcn_sched_barrier(0);
; #pragma unroll
;         for (int j = 0; j < 4; ++j) wa[j] = lds16(wr + (j * 16) * GST + 32);
;         __builtin_amdgcn_sched_barrier(0);
; #pragma unroll
;         for (int j = 0; j < 4; ++j)
; #pragma unroll
;             for (int i = 0; i < MI; ++i) acc[i][j + 4] = mfma16(wb[j], __builtin_bit_cast(bf16x8, ra[i][0]), acc[i][j + 4]);
;         __builtin_amdgcn_sched_barrier(0);
; #pragma unroll
;         for (int i = 0; i < MI; ++i) ra[i][0] = *(const u32x4*)(ap + (size_t)i * ASI + ka);
; #pragma unroll
;         for (int j = 0; j < 4; ++j) wb[j] = lds16(wr + ((j + 4) * 16) * GST + 32);
;         __builtin_amdgcn_sched_barrier(0);
; #pragma unroll
;         for (int j = 0; j < 4; ++j)
; #pragma unroll
;             for (int i = 0; i < MI; ++i) acc[i][j] = mfma16(wa[j], __builtin_bit_cast(bf16x8, ra[i][1]), acc[i][j]);
;         __builtin_amdgcn_sched_barrier(0);
; #pragma unroll
;         for (int j = 0; j < 4; ++j)
; #pragma unroll
;             for (int i = 0; i < MI; ++i) acc[i][j + 4] = mfma16(wb[j], __builtin_bit_cast(bf16x8, ra[i][1]), acc[i][j + 4]);
;         __builtin_amdgcn_s_setprio(0);
;         __builtin_amdgcn_sched_barrier(0);
; #pragma unroll
;         for (int i = 0; i < MI; ++i) ra[i][1] = *(const u32x4*)(ap + (size_t)i * ASI + ka + ASK);
;     }
.LBB0_224:
	v_add_co_u32_e32 v176, vcc, s37, v170
	s_cmpk_lg_i32 s6, 0xb00
	s_nop 0
	v_addc_co_u32_e32 v177, vcc, 0, v171, vcc
	v_add_co_u32_e32 v180, vcc, s11, v170
	global_load_dwordx4 v[172:175], v[170:171], off offset:1024
	s_nop 0
	v_addc_co_u32_e32 v181, vcc, 0, v171, vcc
	v_add_co_u32_e32 v170, vcc, s33, v170
	s_cselect_b32 s78, s6, 0xac0
	s_nop 0
	v_addc_co_u32_e32 v171, vcc, 0, v171, vcc
	global_load_dwordx4 v[176:179], v[176:177], off offset:1024
	s_nop 0
	global_load_dwordx4 v[180:183], v[180:181], off offset:1024
	s_nop 0
	global_load_dwordx4 v[184:187], v[170:171], off offset:1024
	s_barrier
	s_waitcnt vmcnt(9)
	ds_write_b128 v164, v[136:139]
	ds_write_b128 v164, v[124:127] offset:4608
	ds_write_b128 v164, v[128:131] offset:9216
	s_waitcnt vmcnt(7)
	ds_write_b128 v164, v[144:147] offset:13824
	v_lshl_add_u64 v[124:125], s[78:79], 1, v[160:161]
	v_add_co_u32_e32 v126, vcc, s11, v124
	s_waitcnt lgkmcnt(0)
	s_nop 0
	v_addc_co_u32_e32 v127, vcc, 0, v125, vcc
	v_add_co_u32_e32 v128, vcc, s35, v124
	s_barrier
	s_nop 0
	v_addc_co_u32_e32 v129, vcc, 0, v125, vcc
	v_add_co_u32_e32 v144, vcc, s36, v124
	s_nop 1
	v_addc_co_u32_e32 v145, vcc, 0, v125, vcc
	global_load_dwordx4 v[136:139], v[124:125], off
	s_nop 0
	global_load_dwordx4 v[124:127], v[126:127], off
	s_nop 0
	global_load_dwordx4 v[128:131], v[128:129], off
	s_nop 0
	global_load_dwordx4 v[144:147], v[144:145], off
	ds_read_b128 v[188:191], v169
	ds_read_b128 v[220:223], v169 offset:2304
	ds_read_b128 v[224:227], v169 offset:4608
	ds_read_b128 v[228:231], v169 offset:6912
	ds_read_b128 v[232:235], v169 offset:9216
	ds_read_b128 v[236:239], v169 offset:11520
	ds_read_b128 v[240:243], v169 offset:13824
	ds_read_b128 v[244:247], v169 offset:16128
	s_setprio 1
	s_waitcnt vmcnt(9) lgkmcnt(7)
	v_mfma_f32_16x16x32_bf16 v[156:159], v[188:191], v[112:115], v[156:159]
	s_waitcnt vmcnt(10)
	v_mfma_f32_16x16x32_bf16 v[92:95], v[188:191], v[116:119], v[92:95]
	s_waitcnt vmcnt(9)
	v_mfma_f32_16x16x32_bf16 v[60:63], v[188:191], v[120:123], v[60:63]
	s_waitcnt vmcnt(8)
	v_mfma_f32_16x16x32_bf16 v[28:31], v[188:191], v[132:135], v[28:31]
	s_waitcnt lgkmcnt(6)
	v_mfma_f32_16x16x32_bf16 v[152:155], v[220:223], v[112:115], v[152:155]
	v_mfma_f32_16x16x32_bf16 v[88:91], v[220:223], v[116:119], v[88:91]
	v_mfma_f32_16x16x32_bf16 v[56:59], v[220:223], v[120:123], v[56:59]
	v_mfma_f32_16x16x32_bf16 v[24:27], v[220:223], v[132:135], v[24:27]
	s_waitcnt lgkmcnt(5)
	v_mfma_f32_16x16x32_bf16 v[148:151], v[224:227], v[112:115], v[148:151]
	v_mfma_f32_16x16x32_bf16 v[84:87], v[224:227], v[116:119], v[84:87]
	v_mfma_f32_16x16x32_bf16 v[52:55], v[224:227], v[120:123], v[52:55]
	v_mfma_f32_16x16x32_bf16 v[20:23], v[224:227], v[132:135], v[20:23]
	s_waitcnt lgkmcnt(4)
	v_mfma_f32_16x16x32_bf16 v[140:143], v[228:231], v[112:115], v[140:143]
	v_mfma_f32_16x16x32_bf16 v[80:83], v[228:231], v[116:119], v[80:83]
	v_mfma_f32_16x16x32_bf16 v[48:51], v[228:231], v[120:123], v[48:51]
	v_mfma_f32_16x16x32_bf16 v[16:19], v[228:231], v[132:135], v[16:19]
	ds_read_b128 v[188:191], v169 offset:64
	ds_read_b128 v[220:223], v169 offset:2368
	ds_read_b128 v[224:227], v169 offset:4672
	ds_read_b128 v[228:231], v169 offset:6976
	s_waitcnt lgkmcnt(7)
	v_mfma_f32_16x16x32_bf16 v[108:111], v[232:235], v[112:115], v[108:111]
	v_mfma_f32_16x16x32_bf16 v[76:79], v[232:235], v[116:119], v[76:79]
	v_mfma_f32_16x16x32_bf16 v[44:47], v[232:235], v[120:123], v[44:47]
	v_mfma_f32_16x16x32_bf16 v[12:15], v[232:235], v[132:135], v[12:15]
	s_waitcnt lgkmcnt(6)
	v_mfma_f32_16x16x32_bf16 v[104:107], v[236:239], v[112:115], v[104:107]
	v_mfma_f32_16x16x32_bf16 v[72:75], v[236:239], v[116:119], v[72:75]
	v_mfma_f32_16x16x32_bf16 v[40:43], v[236:239], v[120:123], v[40:43]
	v_mfma_f32_16x16x32_bf16 v[8:11], v[236:239], v[132:135], v[8:11]
	s_waitcnt lgkmcnt(5)
	v_mfma_f32_16x16x32_bf16 v[100:103], v[240:243], v[112:115], v[100:103]
	v_mfma_f32_16x16x32_bf16 v[68:71], v[240:243], v[116:119], v[68:71]
	v_mfma_f32_16x16x32_bf16 v[36:39], v[240:243], v[120:123], v[36:39]
	v_mfma_f32_16x16x32_bf16 v[4:7], v[240:243], v[132:135], v[4:7]
	s_waitcnt lgkmcnt(4)
	v_mfma_f32_16x16x32_bf16 v[96:99], v[244:247], v[112:115], v[96:99]
	v_mfma_f32_16x16x32_bf16 v[64:67], v[244:247], v[116:119], v[64:67]
	v_mfma_f32_16x16x32_bf16 v[32:35], v[244:247], v[120:123], v[32:35]
	v_mfma_f32_16x16x32_bf16 v[0:3], v[244:247], v[132:135], v[0:3]
	s_lshl_b32 s78, s78, 5
	v_lshl_add_u64 v[170:171], v[162:163], 0, s[78:79]
	v_add_co_u32_e32 v112, vcc, s37, v170
	s_nop 1
	v_addc_co_u32_e32 v113, vcc, 0, v171, vcc
	v_add_co_u32_e32 v114, vcc, s11, v170
	s_nop 1
	v_addc_co_u32_e32 v115, vcc, 0, v171, vcc
	v_add_co_u32_e32 v132, vcc, s33, v170
	global_load_dwordx4 v[116:119], v[112:113], off
	global_load_dwordx4 v[120:123], v[114:115], off
	v_addc_co_u32_e32 v133, vcc, 0, v171, vcc
	global_load_dwordx4 v[112:115], v[170:171], off
	s_nop 0
	global_load_dwordx4 v[132:135], v[132:133], off
	ds_read_b128 v[232:235], v169 offset:9280
	ds_read_b128 v[236:239], v169 offset:11584
	ds_read_b128 v[240:243], v169 offset:13888
	ds_read_b128 v[244:247], v169 offset:16192
	s_waitcnt vmcnt(11) lgkmcnt(7)
	v_mfma_f32_16x16x32_bf16 v[156:159], v[188:191], v[172:175], v[156:159]
	s_waitcnt vmcnt(10)
	v_mfma_f32_16x16x32_bf16 v[92:95], v[188:191], v[176:179], v[92:95]
	s_waitcnt vmcnt(9)
	v_mfma_f32_16x16x32_bf16 v[60:63], v[188:191], v[180:183], v[60:63]
	s_waitcnt vmcnt(8)
	v_mfma_f32_16x16x32_bf16 v[28:31], v[188:191], v[184:187], v[28:31]
	s_waitcnt lgkmcnt(6)
; __device__ __forceinline__ f32x4 mfma16(bf16x8 a, bf16x8 b, f32x4 c) { return __builtin_amdgcn_mfma_f32_16x16x32_bf16(a, b, c, 0, 0, 0); }
;     ...
;         for (int j = 0; j < 4; ++j)
; #pragma unroll
;             for (int i = 0; i < MI; ++i) acc[i][j] = mfma16(wa[j], __builtin_bit_cast(bf16x8, ra[i][1]), acc[i][j]);
;         __builtin_amdgcn_sched_barrier(0);
; #pragma unroll
;         for (int j = 0; j < 4; ++j)
; #pragma unroll
;             for (int i = 0; i < MI; ++i) acc[i][j + 4] = mfma16(wb[j], __builtin_bit_cast(bf16x8, ra[i][1]), acc[i][j + 4]);
;         __builtin_amdgcn_s_setprio(0);
;         __builtin_amdgcn_sched_barrier(0);
; #pragma unroll
;         for (int i = 0; i < MI; ++i) ra[i][1] = *(const u32x4*)(ap + (size_t)i * ASI + ka + ASK);
;     }
	v_mfma_f32_16x16x32_bf16 v[152:155], v[220:223], v[172:175], v[152:155]
	v_mfma_f32_16x16x32_bf16 v[88:91], v[220:223], v[176:179], v[88:91]
	v_mfma_f32_16x16x32_bf16 v[56:59], v[220:223], v[180:183], v[56:59]
	v_mfma_f32_16x16x32_bf16 v[24:27], v[220:223], v[184:187], v[24:27]
	s_waitcnt lgkmcnt(5)
	v_mfma_f32_16x16x32_bf16 v[148:151], v[224:227], v[172:175], v[148:151]
	v_mfma_f32_16x16x32_bf16 v[84:87], v[224:227], v[176:179], v[84:87]
	v_mfma_f32_16x16x32_bf16 v[52:55], v[224:227], v[180:183], v[52:55]
	v_mfma_f32_16x16x32_bf16 v[20:23], v[224:227], v[184:187], v[20:23]
	s_waitcnt lgkmcnt(4)
	v_mfma_f32_16x16x32_bf16 v[140:143], v[228:231], v[172:175], v[140:143]
	v_mfma_f32_16x16x32_bf16 v[80:83], v[228:231], v[176:179], v[80:83]
	v_mfma_f32_16x16x32_bf16 v[48:51], v[228:231], v[180:183], v[48:51]
	v_mfma_f32_16x16x32_bf16 v[16:19], v[228:231], v[184:187], v[16:19]
	s_waitcnt lgkmcnt(3)
	v_mfma_f32_16x16x32_bf16 v[108:111], v[232:235], v[172:175], v[108:111]
	v_mfma_f32_16x16x32_bf16 v[76:79], v[232:235], v[176:179], v[76:79]
	v_mfma_f32_16x16x32_bf16 v[44:47], v[232:235], v[180:183], v[44:47]
	v_mfma_f32_16x16x32_bf16 v[12:15], v[232:235], v[184:187], v[12:15]
	s_waitcnt lgkmcnt(2)
	v_mfma_f32_16x16x32_bf16 v[104:107], v[236:239], v[172:175], v[104:107]
	v_mfma_f32_16x16x32_bf16 v[72:75], v[236:239], v[176:179], v[72:75]
	v_mfma_f32_16x16x32_bf16 v[40:43], v[236:239], v[180:183], v[40:43]
	v_mfma_f32_16x16x32_bf16 v[8:11], v[236:239], v[184:187], v[8:11]
	s_waitcnt lgkmcnt(1)
	v_mfma_f32_16x16x32_bf16 v[100:103], v[240:243], v[172:175], v[100:103]
	v_mfma_f32_16x16x32_bf16 v[68:71], v[240:243], v[176:179], v[68:71]
	v_mfma_f32_16x16x32_bf16 v[36:39], v[240:243], v[180:183], v[36:39]
	v_mfma_f32_16x16x32_bf16 v[4:7], v[240:243], v[184:187], v[4:7]
	s_waitcnt lgkmcnt(0)
	v_mfma_f32_16x16x32_bf16 v[96:99], v[244:247], v[172:175], v[96:99]
	v_mfma_f32_16x16x32_bf16 v[64:67], v[244:247], v[176:179], v[64:67]
	v_mfma_f32_16x16x32_bf16 v[32:35], v[244:247], v[180:183], v[32:35]
	v_mfma_f32_16x16x32_bf16 v[0:3], v[244:247], v[184:187], v[0:3]
	s_setprio 0
	s_add_i32 s6, s6, 64
	s_cmpk_lg_i32 s6, 0xb40
	s_cbranch_scc1 .LBB0_224
; __device__ __forceinline__ int tid_() { int t = threadIdx.x; asm volatile("" : "+v"(t)); return t; }
; template <int MI>
; __device__ __forceinline__ void epi_resid(CParams& p, int m0, int n0, const f32x4 (&acc)[MI][8], const float* gate  ) {
;     const int lane = tid_() & 63, wave = tid_() >> 6, l16 = lane & 15, quad = lane >> 4;
; #pragma unroll
;     for (int i = 0; i < MI; ++i) {
;         const int row = m0 + wave * 16 * MI + i * 16 + l16;
;         float* xr = xrow(p, row);
;         const float* g = gate + (size_t)seg_of(row) * 6144;
;         float ss = 0.f;
; #pragma unroll
;         for (int j = 0; j < 8; ++j) {
;             const int col = n0 + j * 16 + quad * 4;
;             const f32x4 gv = *(const f32x4*)(g + col);
;             f32x4 xv = *(f32x4*)(xr + col);
;             xv += gv * acc[i][j];
;             *(f32x4*)(xr + col) = xv;
;             ss += xv[0] * xv[0] + xv[1] * xv[1] + xv[2] * xv[2] + xv[3] * xv[3];
;         }
;         ss += __shfl_xor(ss, 16); ss += __shfl_xor(ss, 32);
;         if (quad == 0) ((float*)(p.ws + WS_PART))[(size_t)row * 8 + (n0 >> 7)] = ss;
;         __builtin_amdgcn_sched_barrier(0);
;     }
	s_waitcnt vmcnt(1)
	v_mov_b32_e32 v112, v167
	v_mov_b32_e32 v113, v167
	s_lshl_b32 s5, s5, 8
	v_mov_b32_e32 v118, s16
	v_bfe_u32 v117, v112, 4, 2
	v_and_b32_e32 v113, 0xffffffc0, v113
	v_and_or_b32 v112, v112, 15, s5
	v_add_u32_e32 v112, v112, v113
	v_ashrrev_i32_e32 v113, 31, v112
	v_cmp_gt_i32_e32 vcc, s34, v112
	v_subrev_co_u32_e64 v114, s[42:43], s34, v112
	v_mov_b32_e32 v119, s45
	v_cndmask_b32_e32 v115, 0, v113, vcc
	v_cndmask_b32_e32 v114, v114, v112, vcc
	v_cndmask_b32_e32 v119, v118, v119, vcc
	v_mov_b32_e32 v118, s15
	v_mov_b32_e32 v121, s44
	s_movk_i32 s2, 0x1fff
	v_cndmask_b32_e64 v116, v213, v214, s[42:43]
	v_cndmask_b32_e32 v118, v118, v121, vcc
	v_lshlrev_b64 v[114:115], 12, v[114:115]
	v_cmp_lt_i32_e32 vcc, s2, v112
	s_lshl_b32 s6, s4, 7
	v_lshl_add_u64 v[114:115], v[118:119], 0, v[114:115]
	v_cndmask_b32_e32 v118, 0, v116, vcc
	v_lshl_or_b32 v120, v117, 2, s6
	v_lshlrev_b32_e32 v164, 2, v118
	v_lshl_add_u64 v[118:119], s[48:49], 0, v[164:165]
	v_lshlrev_b32_e32 v164, 2, v120
	v_lshl_add_u64 v[146:147], v[118:119], 0, v[164:165]
	v_lshl_add_u64 v[114:115], v[114:115], 0, v[164:165]
	global_load_dwordx4 v[160:163], v[146:147], off
	global_load_dwordx4 v[172:175], v[114:115], off
	global_load_dwordx4 v[176:179], v[114:115], off offset:64
	global_load_dwordx4 v[180:183], v[146:147], off offset:64
	global_load_dwordx4 v[184:187], v[146:147], off offset:128
	global_load_dwordx4 v[188:191], v[114:115], off offset:128
	global_load_dwordx4 v[220:223], v[114:115], off offset:192
	global_load_dwordx4 v[224:227], v[146:147], off offset:192
	global_load_dwordx4 v[228:231], v[146:147], off offset:256
	global_load_dwordx4 v[232:235], v[114:115], off offset:256
	global_load_dwordx4 v[236:239], v[114:115], off offset:320
	global_load_dwordx4 v[240:243], v[146:147], off offset:320
	v_cmp_lt_i32_e32 vcc, v204, v199
	s_lshl_b32 s4, s4, 2
	s_add_u32 s4, s46, s4
	s_addc_u32 s5, s47, 0
	s_waitcnt vmcnt(10)
	v_pk_fma_f32 v[120:121], v[158:159], v[162:163], v[174:175]
	v_pk_fma_f32 v[118:119], v[156:157], v[160:161], v[172:173]
	global_store_dwordx4 v[114:115], v[118:121], off
	s_waitcnt vmcnt(8)
	v_pk_fma_f32 v[124:125], v[154:155], v[182:183], v[178:179]
	v_pk_fma_f32 v[122:123], v[152:153], v[180:181], v[176:177]
	global_store_dwordx4 v[114:115], v[122:125], off offset:64
	s_waitcnt vmcnt(6)
	v_pk_fma_f32 v[128:129], v[150:151], v[186:187], v[190:191]
	v_pk_fma_f32 v[126:127], v[148:149], v[184:185], v[188:189]
	global_store_dwordx4 v[114:115], v[126:129], off offset:128
	s_waitcnt vmcnt(4)
	v_pk_fma_f32 v[132:133], v[142:143], v[226:227], v[222:223]
	v_pk_fma_f32 v[130:131], v[140:141], v[224:225], v[220:221]
	global_store_dwordx4 v[114:115], v[130:133], off offset:192
	s_waitcnt vmcnt(2)
	v_pk_fma_f32 v[110:111], v[110:111], v[230:231], v[234:235]
	v_pk_fma_f32 v[108:109], v[108:109], v[228:229], v[232:233]
	global_store_dwordx4 v[114:115], v[108:111], off offset:256
	s_waitcnt vmcnt(0)
	v_pk_fma_f32 v[106:107], v[106:107], v[242:243], v[238:239]
	v_pk_fma_f32 v[104:105], v[104:105], v[240:241], v[236:237]
	global_store_dwordx4 v[114:115], v[104:107], off offset:320
	global_load_dwordx4 v[134:137], v[146:147], off offset:384
	global_load_dwordx4 v[138:141], v[114:115], off offset:384
	global_load_dwordx4 v[142:145], v[114:115], off offset:448
	s_waitcnt vmcnt(1)
	v_pk_fma_f32 v[136:137], v[102:103], v[136:137], v[140:141]
	v_pk_fma_f32 v[134:135], v[100:101], v[134:135], v[138:139]
	global_store_dwordx4 v[114:115], v[134:137], off offset:384
	global_load_dwordx4 v[138:141], v[146:147], off offset:448
	v_cndmask_b32_e32 v100, v197, v204, vcc
	v_lshlrev_b32_e32 v102, 2, v100
	v_mul_f32_e32 v100, v119, v119
	v_mul_f32_e32 v101, v123, v123
	v_fmac_f32_e32 v100, v118, v118
	v_fmac_f32_e32 v101, v122, v122
	v_fmac_f32_e32 v100, v120, v120
	v_fmac_f32_e32 v101, v124, v124
	v_fmac_f32_e32 v100, v121, v121
	v_fmac_f32_e32 v101, v125, v125
	v_add_f32_e32 v100, v100, v101
	v_mul_f32_e32 v101, v127, v127
	v_fmac_f32_e32 v101, v126, v126
	v_fmac_f32_e32 v101, v128, v128
	v_fmac_f32_e32 v101, v129, v129
	v_add_f32_e32 v100, v100, v101
	v_mul_f32_e32 v101, v131, v131
	v_fmac_f32_e32 v101, v130, v130
	v_fmac_f32_e32 v101, v132, v132
	v_fmac_f32_e32 v101, v133, v133
	v_add_f32_e32 v100, v100, v101
	v_mul_f32_e32 v101, v109, v109
	v_fmac_f32_e32 v101, v108, v108
	v_fmac_f32_e32 v101, v110, v110
	v_fmac_f32_e32 v101, v111, v111
	v_add_f32_e32 v100, v100, v101
	v_mul_f32_e32 v101, v105, v105
	v_fmac_f32_e32 v101, v104, v104
	v_fmac_f32_e32 v101, v106, v106
	v_fmac_f32_e32 v101, v107, v107
	v_add_f32_e32 v100, v100, v101
	v_mul_f32_e32 v101, v135, v135
	v_fmac_f32_e32 v101, v134, v134
	v_fmac_f32_e32 v101, v136, v136
	v_fmac_f32_e32 v101, v137, v137
	v_add_f32_e32 v103, v100, v101
	v_cmp_lt_i32_e32 vcc, v205, v199
	s_waitcnt vmcnt(0)
	v_pk_fma_f32 v[100:101], v[98:99], v[140:141], v[144:145]
	v_pk_fma_f32 v[98:99], v[96:97], v[138:139], v[142:143]
	global_store_dwordx4 v[114:115], v[98:101], off offset:448
	v_mul_f32_e32 v96, v99, v99
	v_fmac_f32_e32 v96, v98, v98
	v_fmac_f32_e32 v96, v100, v100
	v_fmac_f32_e32 v96, v101, v101
	v_add_f32_e32 v96, v103, v96
	ds_bpermute_b32 v97, v102, v96
	v_cndmask_b32_e32 v103, v197, v205, vcc
	v_lshlrev_b32_e32 v103, 2, v103
	v_cmp_eq_u32_e32 vcc, 0, v117
	s_waitcnt lgkmcnt(0)
	v_add_f32_e32 v96, v96, v97
	ds_bpermute_b32 v97, v103, v96
	s_and_saveexec_b64 s[6:7], vcc
	s_cbranch_execz .LBB0_227
	v_lshlrev_b64 v[98:99], 5, v[112:113]
	v_lshl_add_u64 v[98:99], s[4:5], 0, v[98:99]
	s_waitcnt lgkmcnt(0)
	v_add_f32_e32 v96, v96, v97
	global_store_dword v[98:99], v96, off

; __device__ __forceinline__ f32x4 mfma16(bf16x8 a, bf16x8 b, f32x4 c) { return __builtin_amdgcn_mfma_f32_16x16x32_bf16(a, b, c, 0, 0, 0); }
;     ...
;     for (int kt = 0; kt < nk; ++kt) {
;         lds_sync();
; #pragma unroll
;         for (int i = 0; i < 4; ++i) *(u32x4*)(sW + (srow + i * 32) * GST + skc) = rw[i];
;         lds_sync();
;         const int k0 = (kt + 1 < nk ? kt + 1 : kt) << 6;
;         const int ka = FRAG ? (k0 >> 5) * 512 : k0;
; #pragma unroll
;         for (int i = 0; i < 4; ++i) rw[i] = *(const u32x4*)(wp + (size_t)(i * 32) * ldw + k0);
;         bf16x8 wa[4], wb[4];
; #pragma unroll
;         for (int j = 0; j < 4; ++j) wa[j] = lds16(wr + (j * 16) * GST);
; #pragma unroll
;         for (int j = 0; j < 4; ++j) wb[j] = lds16(wr + ((j + 4) * 16) * GST);
;         __builtin_amdgcn_sched_barrier(0);
;         __builtin_amdgcn_s_setprio(1);
; #pragma unroll
;         for (int j = 0; j < 4; ++j)
; #pragma unroll
;             for (int i = 0; i < MI; ++i) acc[i][j] = mfma16(wa[j], __builtin_bit_cast(bf16x8, ra[i][0]), acc[i][j]);
;         __builtin_amdgcn_sched_barrier(0);
; #pragma unroll
;         for (int j = 0; j < 4; ++j) wa[j] = lds16(wr + (j * 16) * GST + 32);
;         __builtin_amdgcn_sched_barrier(0);
; #pragma unroll
;         for (int j = 0; j < 4; ++j)
; #pragma unroll
;             for (int i = 0; i < MI; ++i) acc[i][j + 4] = mfma16(wb[j], __builtin_bit_cast(bf16x8, ra[i][0]), acc[i][j + 4]);
;         __builtin_amdgcn_sched_barrier(0);
; #pragma unroll
;         for (int i = 0; i < MI; ++i) ra[i][0] = *(const u32x4*)(ap + (size_t)i * ASI + ka);
; #pragma unroll
;         for (int j = 0; j < 4; ++j) wb[j] = lds16(wr + ((j + 4) * 16) * GST + 32);
;         __builtin_amdgcn_sched_barrier(0);
; #pragma unroll
;         for (int j = 0; j < 4; ++j)
; #pragma unroll
;             for (int i = 0; i < MI; ++i) acc[i][j] = mfma16(wa[j], __builtin_bit_cast(bf16x8, ra[i][1]), acc[i][j]);
;         __builtin_amdgcn_sched_barrier(0);
; #pragma unroll
;         for (int j = 0; j < 4; ++j)
; #pragma unroll
;             for (int i = 0; i < MI; ++i) acc[i][j + 4] = mfma16(wb[j], __builtin_bit_cast(bf16x8, ra[i][1]), acc[i][j + 4]);
;         __builtin_amdgcn_s_setprio(0);
;         __builtin_amdgcn_sched_barrier(0);
; #pragma unroll
;         for (int i = 0; i < MI; ++i) ra[i][1] = *(const u32x4*)(ap + (size_t)i * ASI + ka + ASK);
;     }
.LBB0_525:
	v_add_co_u32_e32 v176, vcc, s97, v170
	s_cmpk_lg_i32 s5, 0x800
	s_nop 0
	v_addc_co_u32_e32 v177, vcc, 0, v171, vcc
	v_add_co_u32_e32 v180, vcc, s80, v170
	global_load_dwordx4 v[172:175], v[170:171], off offset:1024
	s_nop 0
	v_addc_co_u32_e32 v181, vcc, 0, v171, vcc
	v_add_co_u32_e32 v170, vcc, s86, v170
	s_cselect_b32 s78, s5, 0x7c0
	s_nop 0
	v_addc_co_u32_e32 v171, vcc, 0, v171, vcc
	global_load_dwordx4 v[176:179], v[176:177], off offset:1024
	s_nop 0
	global_load_dwordx4 v[180:183], v[180:181], off offset:1024
	s_nop 0
	global_load_dwordx4 v[184:187], v[170:171], off offset:1024
	s_barrier
	s_waitcnt vmcnt(9)
	ds_write_b128 v164, v[136:139]
	ds_write_b128 v164, v[124:127] offset:4608
	ds_write_b128 v164, v[128:131] offset:9216
	s_waitcnt vmcnt(7)
	ds_write_b128 v164, v[144:147] offset:13824
	v_lshl_add_u64 v[124:125], s[78:79], 1, v[160:161]
	v_add_co_u32_e32 v126, vcc, s80, v124
	s_waitcnt lgkmcnt(0)
	s_nop 0
	v_addc_co_u32_e32 v127, vcc, 0, v125, vcc
	v_add_co_u32_e32 v128, vcc, s82, v124
	s_barrier
	s_nop 0
	v_addc_co_u32_e32 v129, vcc, 0, v125, vcc
	v_add_co_u32_e32 v144, vcc, s83, v124
	s_nop 1
	v_addc_co_u32_e32 v145, vcc, 0, v125, vcc
	global_load_dwordx4 v[136:139], v[124:125], off
	s_nop 0
	global_load_dwordx4 v[124:127], v[126:127], off
	s_nop 0
	global_load_dwordx4 v[128:131], v[128:129], off
	s_nop 0
	global_load_dwordx4 v[144:147], v[144:145], off
	ds_read_b128 v[188:191], v169
	ds_read_b128 v[220:223], v169 offset:2304
	ds_read_b128 v[224:227], v169 offset:4608
	ds_read_b128 v[228:231], v169 offset:6912
	ds_read_b128 v[232:235], v169 offset:9216
	ds_read_b128 v[236:239], v169 offset:11520
	ds_read_b128 v[240:243], v169 offset:13824
	ds_read_b128 v[244:247], v169 offset:16128
	s_setprio 1
	s_waitcnt vmcnt(9) lgkmcnt(7)
	v_mfma_f32_16x16x32_bf16 v[156:159], v[188:191], v[112:115], v[156:159]
	s_waitcnt vmcnt(10)
	v_mfma_f32_16x16x32_bf16 v[92:95], v[188:191], v[116:119], v[92:95]
	s_waitcnt vmcnt(9)
	v_mfma_f32_16x16x32_bf16 v[60:63], v[188:191], v[120:123], v[60:63]
	s_waitcnt vmcnt(8)
	v_mfma_f32_16x16x32_bf16 v[28:31], v[188:191], v[132:135], v[28:31]
	s_waitcnt lgkmcnt(6)
	v_mfma_f32_16x16x32_bf16 v[152:155], v[220:223], v[112:115], v[152:155]
	v_mfma_f32_16x16x32_bf16 v[88:91], v[220:223], v[116:119], v[88:91]
	v_mfma_f32_16x16x32_bf16 v[56:59], v[220:223], v[120:123], v[56:59]
	v_mfma_f32_16x16x32_bf16 v[24:27], v[220:223], v[132:135], v[24:27]
	s_waitcnt lgkmcnt(5)
	v_mfma_f32_16x16x32_bf16 v[148:151], v[224:227], v[112:115], v[148:151]
	v_mfma_f32_16x16x32_bf16 v[84:87], v[224:227], v[116:119], v[84:87]
	v_mfma_f32_16x16x32_bf16 v[52:55], v[224:227], v[120:123], v[52:55]
	v_mfma_f32_16x16x32_bf16 v[20:23], v[224:227], v[132:135], v[20:23]
	s_waitcnt lgkmcnt(4)
	v_mfma_f32_16x16x32_bf16 v[140:143], v[228:231], v[112:115], v[140:143]
	v_mfma_f32_16x16x32_bf16 v[80:83], v[228:231], v[116:119], v[80:83]
	v_mfma_f32_16x16x32_bf16 v[48:51], v[228:231], v[120:123], v[48:51]
	v_mfma_f32_16x16x32_bf16 v[16:19], v[228:231], v[132:135], v[16:19]
	ds_read_b128 v[188:191], v169 offset:64
	ds_read_b128 v[220:223], v169 offset:2368
	ds_read_b128 v[224:227], v169 offset:4672
	ds_read_b128 v[228:231], v169 offset:6976
	s_waitcnt lgkmcnt(7)
	v_mfma_f32_16x16x32_bf16 v[108:111], v[232:235], v[112:115], v[108:111]
	v_mfma_f32_16x16x32_bf16 v[76:79], v[232:235], v[116:119], v[76:79]
	v_mfma_f32_16x16x32_bf16 v[44:47], v[232:235], v[120:123], v[44:47]
	v_mfma_f32_16x16x32_bf16 v[12:15], v[232:235], v[132:135], v[12:15]
	s_waitcnt lgkmcnt(6)
	v_mfma_f32_16x16x32_bf16 v[104:107], v[236:239], v[112:115], v[104:107]
	v_mfma_f32_16x16x32_bf16 v[72:75], v[236:239], v[116:119], v[72:75]
	v_mfma_f32_16x16x32_bf16 v[40:43], v[236:239], v[120:123], v[40:43]
	v_mfma_f32_16x16x32_bf16 v[8:11], v[236:239], v[132:135], v[8:11]
	s_waitcnt lgkmcnt(5)
	v_mfma_f32_16x16x32_bf16 v[100:103], v[240:243], v[112:115], v[100:103]
	v_mfma_f32_16x16x32_bf16 v[68:71], v[240:243], v[116:119], v[68:71]
	v_mfma_f32_16x16x32_bf16 v[36:39], v[240:243], v[120:123], v[36:39]
	v_mfma_f32_16x16x32_bf16 v[4:7], v[240:243], v[132:135], v[4:7]
	s_waitcnt lgkmcnt(4)
	v_mfma_f32_16x16x32_bf16 v[96:99], v[244:247], v[112:115], v[96:99]
	v_mfma_f32_16x16x32_bf16 v[64:67], v[244:247], v[116:119], v[64:67]
	v_mfma_f32_16x16x32_bf16 v[32:35], v[244:247], v[120:123], v[32:35]
	v_mfma_f32_16x16x32_bf16 v[0:3], v[244:247], v[132:135], v[0:3]
	s_lshl_b32 s78, s78, 5
	v_lshl_add_u64 v[170:171], v[162:163], 0, s[78:79]
	v_add_co_u32_e32 v112, vcc, s97, v170
	s_nop 1
	v_addc_co_u32_e32 v113, vcc, 0, v171, vcc
	v_add_co_u32_e32 v114, vcc, s80, v170
	s_nop 1
	v_addc_co_u32_e32 v115, vcc, 0, v171, vcc
	v_add_co_u32_e32 v132, vcc, s86, v170
	global_load_dwordx4 v[116:119], v[112:113], off
	global_load_dwordx4 v[120:123], v[114:115], off
	v_addc_co_u32_e32 v133, vcc, 0, v171, vcc
	global_load_dwordx4 v[112:115], v[170:171], off
	s_nop 0
	global_load_dwordx4 v[132:135], v[132:133], off
	ds_read_b128 v[232:235], v169 offset:9280
	ds_read_b128 v[236:239], v169 offset:11584
	ds_read_b128 v[240:243], v169 offset:13888
	ds_read_b128 v[244:247], v169 offset:16192
	s_waitcnt vmcnt(11) lgkmcnt(7)
	v_mfma_f32_16x16x32_bf16 v[156:159], v[188:191], v[172:175], v[156:159]
	s_waitcnt vmcnt(10)
	v_mfma_f32_16x16x32_bf16 v[92:95], v[188:191], v[176:179], v[92:95]
	s_waitcnt vmcnt(9)
	v_mfma_f32_16x16x32_bf16 v[60:63], v[188:191], v[180:183], v[60:63]
	s_waitcnt vmcnt(8)
	v_mfma_f32_16x16x32_bf16 v[28:31], v[188:191], v[184:187], v[28:31]
	s_waitcnt lgkmcnt(6)
; __device__ __forceinline__ f32x4 mfma16(bf16x8 a, bf16x8 b, f32x4 c) { return __builtin_amdgcn_mfma_f32_16x16x32_bf16(a, b, c, 0, 0, 0); }
;     ...
;         for (int j = 0; j < 4; ++j)
; #pragma unroll
;             for (int i = 0; i < MI; ++i) acc[i][j] = mfma16(wa[j], __builtin_bit_cast(bf16x8, ra[i][1]), acc[i][j]);
;         __builtin_amdgcn_sched_barrier(0);
; #pragma unroll
;         for (int j = 0; j < 4; ++j)
; #pragma unroll
;             for (int i = 0; i < MI; ++i) acc[i][j + 4] = mfma16(wb[j], __builtin_bit_cast(bf16x8, ra[i][1]), acc[i][j + 4]);
;         __builtin_amdgcn_s_setprio(0);
;         __builtin_amdgcn_sched_barrier(0);
; #pragma unroll
;         for (int i = 0; i < MI; ++i) ra[i][1] = *(const u32x4*)(ap + (size_t)i * ASI + ka + ASK);
;     }
	v_mfma_f32_16x16x32_bf16 v[152:155], v[220:223], v[172:175], v[152:155]
	v_mfma_f32_16x16x32_bf16 v[88:91], v[220:223], v[176:179], v[88:91]
	v_mfma_f32_16x16x32_bf16 v[56:59], v[220:223], v[180:183], v[56:59]
	v_mfma_f32_16x16x32_bf16 v[24:27], v[220:223], v[184:187], v[24:27]
	s_waitcnt lgkmcnt(5)
	v_mfma_f32_16x16x32_bf16 v[148:151], v[224:227], v[172:175], v[148:151]
	v_mfma_f32_16x16x32_bf16 v[84:87], v[224:227], v[176:179], v[84:87]
	v_mfma_f32_16x16x32_bf16 v[52:55], v[224:227], v[180:183], v[52:55]
	v_mfma_f32_16x16x32_bf16 v[20:23], v[224:227], v[184:187], v[20:23]
	s_waitcnt lgkmcnt(4)
	v_mfma_f32_16x16x32_bf16 v[140:143], v[228:231], v[172:175], v[140:143]
	v_mfma_f32_16x16x32_bf16 v[80:83], v[228:231], v[176:179], v[80:83]
	v_mfma_f32_16x16x32_bf16 v[48:51], v[228:231], v[180:183], v[48:51]
	v_mfma_f32_16x16x32_bf16 v[16:19], v[228:231], v[184:187], v[16:19]
	s_waitcnt lgkmcnt(3)
	v_mfma_f32_16x16x32_bf16 v[108:111], v[232:235], v[172:175], v[108:111]
	v_mfma_f32_16x16x32_bf16 v[76:79], v[232:235], v[176:179], v[76:79]
	v_mfma_f32_16x16x32_bf16 v[44:47], v[232:235], v[180:183], v[44:47]
	v_mfma_f32_16x16x32_bf16 v[12:15], v[232:235], v[184:187], v[12:15]
	s_waitcnt lgkmcnt(2)
	v_mfma_f32_16x16x32_bf16 v[104:107], v[236:239], v[172:175], v[104:107]
	v_mfma_f32_16x16x32_bf16 v[72:75], v[236:239], v[176:179], v[72:75]
	v_mfma_f32_16x16x32_bf16 v[40:43], v[236:239], v[180:183], v[40:43]
	v_mfma_f32_16x16x32_bf16 v[8:11], v[236:239], v[184:187], v[8:11]
	s_waitcnt lgkmcnt(1)
	v_mfma_f32_16x16x32_bf16 v[100:103], v[240:243], v[172:175], v[100:103]
	v_mfma_f32_16x16x32_bf16 v[68:71], v[240:243], v[176:179], v[68:71]
	v_mfma_f32_16x16x32_bf16 v[36:39], v[240:243], v[180:183], v[36:39]
	v_mfma_f32_16x16x32_bf16 v[4:7], v[240:243], v[184:187], v[4:7]
	s_waitcnt lgkmcnt(0)
	v_mfma_f32_16x16x32_bf16 v[96:99], v[244:247], v[172:175], v[96:99]
	v_mfma_f32_16x16x32_bf16 v[64:67], v[244:247], v[176:179], v[64:67]
	v_mfma_f32_16x16x32_bf16 v[32:35], v[244:247], v[180:183], v[32:35]
	v_mfma_f32_16x16x32_bf16 v[0:3], v[244:247], v[184:187], v[0:3]
	s_setprio 0
	s_add_i32 s5, s5, 64
	s_cmpk_lg_i32 s5, 0x840
	s_cbranch_scc1 .LBB0_525
; __device__ __forceinline__ int tid_() { int t = threadIdx.x; asm volatile("" : "+v"(t)); return t; }
; template <int MI>
; __device__ __forceinline__ void epi_resid(CParams& p, int m0, int n0, const f32x4 (&acc)[MI][8], const float* gate  ) {
;     const int lane = tid_() & 63, wave = tid_() >> 6, l16 = lane & 15, quad = lane >> 4;
; #pragma unroll
;     for (int i = 0; i < MI; ++i) {
;         const int row = m0 + wave * 16 * MI + i * 16 + l16;
;         float* xr = xrow(p, row);
;         const float* g = gate + (size_t)seg_of(row) * 6144;
;         float ss = 0.f;
; #pragma unroll
;         for (int j = 0; j < 8; ++j) {
;             const int col = n0 + j * 16 + quad * 4;
;             const f32x4 gv = *(const f32x4*)(g + col);
;             f32x4 xv = *(f32x4*)(xr + col);
;             xv += gv * acc[i][j];
;             *(f32x4*)(xr + col) = xv;
;             ss += xv[0] * xv[0] + xv[1] * xv[1] + xv[2] * xv[2] + xv[3] * xv[3];
;         }
;         ss += __shfl_xor(ss, 16); ss += __shfl_xor(ss, 32);
;         if (quad == 0) ((float*)(p.ws + WS_PART))[(size_t)row * 8 + (n0 >> 7)] = ss;
;         __builtin_amdgcn_sched_barrier(0);
;     }
; }
	s_waitcnt vmcnt(1)
	v_mov_b32_e32 v112, v167
	v_mov_b32_e32 v113, v167
	s_lshl_b32 s4, s4, 8
	v_mov_b32_e32 v118, s16
	v_bfe_u32 v117, v112, 4, 2
	v_and_b32_e32 v113, 0xffffffc0, v113
	v_and_or_b32 v112, v112, 15, s4
	v_add_u32_e32 v112, v112, v113
	v_ashrrev_i32_e32 v113, 31, v112
	v_cmp_gt_i32_e32 vcc, s34, v112
	v_subrev_co_u32_e64 v114, s[42:43], s34, v112
	v_mov_b32_e32 v119, s45
	v_cndmask_b32_e32 v115, 0, v113, vcc
	v_cndmask_b32_e32 v114, v114, v112, vcc
	v_cndmask_b32_e32 v119, v118, v119, vcc
	v_mov_b32_e32 v118, s15
	v_mov_b32_e32 v121, s44
	s_movk_i32 s2, 0x1fff
	v_cndmask_b32_e64 v116, v213, v214, s[42:43]
	v_cndmask_b32_e32 v118, v118, v121, vcc
	v_lshlrev_b64 v[114:115], 12, v[114:115]
	v_cmp_lt_i32_e32 vcc, s2, v112
	s_lshl_b32 s5, s6, 7
	v_lshl_add_u64 v[114:115], v[118:119], 0, v[114:115]
	v_cndmask_b32_e32 v118, 0, v116, vcc
	v_lshl_or_b32 v120, v117, 2, s5
	v_lshlrev_b32_e32 v164, 2, v118
	v_lshl_add_u64 v[118:119], s[48:49], 0, v[164:165]
	v_lshlrev_b32_e32 v164, 2, v120
	v_lshl_add_u64 v[146:147], v[118:119], 0, v[164:165]
	v_lshl_add_u64 v[114:115], v[114:115], 0, v[164:165]
	global_load_dwordx4 v[160:163], v[146:147], off
	global_load_dwordx4 v[172:175], v[114:115], off
	global_load_dwordx4 v[176:179], v[114:115], off offset:64
	global_load_dwordx4 v[180:183], v[146:147], off offset:64
	global_load_dwordx4 v[184:187], v[146:147], off offset:128
	global_load_dwordx4 v[188:191], v[114:115], off offset:128
	global_load_dwordx4 v[220:223], v[114:115], off offset:192
	global_load_dwordx4 v[224:227], v[146:147], off offset:192
	global_load_dwordx4 v[228:231], v[146:147], off offset:256
	global_load_dwordx4 v[232:235], v[114:115], off offset:256
	global_load_dwordx4 v[236:239], v[114:115], off offset:320
	global_load_dwordx4 v[240:243], v[146:147], off offset:320
	v_cmp_lt_i32_e32 vcc, v204, v199
	s_lshl_b32 s4, s6, 2
	s_add_u32 s4, s46, s4
	s_addc_u32 s5, s47, 0
	s_waitcnt vmcnt(10)
	v_pk_fma_f32 v[120:121], v[158:159], v[162:163], v[174:175]
	v_pk_fma_f32 v[118:119], v[156:157], v[160:161], v[172:173]
	global_store_dwordx4 v[114:115], v[118:121], off
	s_waitcnt vmcnt(8)
	v_pk_fma_f32 v[124:125], v[154:155], v[182:183], v[178:179]
	v_pk_fma_f32 v[122:123], v[152:153], v[180:181], v[176:177]
	global_store_dwordx4 v[114:115], v[122:125], off offset:64
	s_waitcnt vmcnt(6)
	v_pk_fma_f32 v[128:129], v[150:151], v[186:187], v[190:191]
	v_pk_fma_f32 v[126:127], v[148:149], v[184:185], v[188:189]
	global_store_dwordx4 v[114:115], v[126:129], off offset:128
	s_waitcnt vmcnt(4)
	v_pk_fma_f32 v[132:133], v[142:143], v[226:227], v[222:223]
	v_pk_fma_f32 v[130:131], v[140:141], v[224:225], v[220:221]
	global_store_dwordx4 v[114:115], v[130:133], off offset:192
	s_waitcnt vmcnt(2)
	v_pk_fma_f32 v[110:111], v[110:111], v[230:231], v[234:235]
	v_pk_fma_f32 v[108:109], v[108:109], v[228:229], v[232:233]
	global_store_dwordx4 v[114:115], v[108:111], off offset:256
	s_waitcnt vmcnt(0)
	v_pk_fma_f32 v[106:107], v[106:107], v[242:243], v[238:239]
	v_pk_fma_f32 v[104:105], v[104:105], v[240:241], v[236:237]
	global_store_dwordx4 v[114:115], v[104:107], off offset:320
	global_load_dwordx4 v[134:137], v[146:147], off offset:384
	global_load_dwordx4 v[138:141], v[114:115], off offset:384
	global_load_dwordx4 v[142:145], v[114:115], off offset:448
	s_waitcnt vmcnt(1)
	v_pk_fma_f32 v[136:137], v[102:103], v[136:137], v[140:141]
	v_pk_fma_f32 v[134:135], v[100:101], v[134:135], v[138:139]
	global_store_dwordx4 v[114:115], v[134:137], off offset:384
	global_load_dwordx4 v[138:141], v[146:147], off offset:448
	v_cndmask_b32_e32 v100, v197, v204, vcc
	v_lshlrev_b32_e32 v102, 2, v100
	v_mul_f32_e32 v100, v119, v119
	v_mul_f32_e32 v101, v123, v123
	v_fmac_f32_e32 v100, v118, v118
	v_fmac_f32_e32 v101, v122, v122
	v_fmac_f32_e32 v100, v120, v120
	v_fmac_f32_e32 v101, v124, v124
	v_fmac_f32_e32 v100, v121, v121
	v_fmac_f32_e32 v101, v125, v125
	v_add_f32_e32 v100, v100, v101
	v_mul_f32_e32 v101, v127, v127
	v_fmac_f32_e32 v101, v126, v126
	v_fmac_f32_e32 v101, v128, v128
	v_fmac_f32_e32 v101, v129, v129
	v_add_f32_e32 v100, v100, v101
	v_mul_f32_e32 v101, v131, v131
	v_fmac_f32_e32 v101, v130, v130
	v_fmac_f32_e32 v101, v132, v132
	v_fmac_f32_e32 v101, v133, v133
	v_add_f32_e32 v100, v100, v101
	v_mul_f32_e32 v101, v109, v109
	v_fmac_f32_e32 v101, v108, v108
	v_fmac_f32_e32 v101, v110, v110
	v_fmac_f32_e32 v101, v111, v111
	v_add_f32_e32 v100, v100, v101
	v_mul_f32_e32 v101, v105, v105
	v_fmac_f32_e32 v101, v104, v104
	v_fmac_f32_e32 v101, v106, v106
	v_fmac_f32_e32 v101, v107, v107
	v_add_f32_e32 v100, v100, v101
	v_mul_f32_e32 v101, v135, v135
	v_fmac_f32_e32 v101, v134, v134
	v_fmac_f32_e32 v101, v136, v136
	v_fmac_f32_e32 v101, v137, v137
	v_add_f32_e32 v103, v100, v101
	v_cmp_lt_i32_e32 vcc, v205, v199
	s_waitcnt vmcnt(0)
	v_pk_fma_f32 v[100:101], v[98:99], v[140:141], v[144:145]
	v_pk_fma_f32 v[98:99], v[96:97], v[138:139], v[142:143]
	global_store_dwordx4 v[114:115], v[98:101], off offset:448
	v_mul_f32_e32 v96, v99, v99
	v_fmac_f32_e32 v96, v98, v98
	v_fmac_f32_e32 v96, v100, v100
	v_fmac_f32_e32 v96, v101, v101
	v_add_f32_e32 v96, v103, v96
	ds_bpermute_b32 v97, v102, v96
	v_cndmask_b32_e32 v103, v197, v205, vcc
	v_lshlrev_b32_e32 v103, 2, v103
	v_cmp_eq_u32_e32 vcc, 0, v117
	s_waitcnt lgkmcnt(0)
	v_add_f32_e32 v96, v96, v97
	ds_bpermute_b32 v97, v103, v96
	s_and_saveexec_b64 s[6:7], vcc
	s_cbranch_execz .LBB0_528
	v_lshlrev_b64 v[98:99], 5, v[112:113]
	v_lshl_add_u64 v[98:99], s[4:5], 0, v[98:99]
	s_waitcnt lgkmcnt(0)
	v_add_f32_e32 v96, v96, v97
	global_store_dword v[98:99], v96, off
